# one static s_setprio 1 for waves 4-7 for the whole kernel, per-segment s_setprio toggling in the GEMM K-loops removed
# speedup vs baseline: 1.0004x; 1.0004x over previous
; #define LAS __attribute__((address_space(3)))
; __device__ __forceinline__ int opaque_tid() { int t = threadIdx.x; asm volatile("" : "+v"(t)); return t; }
; template <class Epi, class Sched, bool ALIGN_EPI = false, bool SP2 = false>
; __device__ __forceinline__ void gemm_phase(PG8_LAS unsigned char* lds, const Gemm g, const Sched& S, const Epi& E) {
;     const int tid = opaque_tid(), wid = __builtin_amdgcn_readfirstlane(tid >> 6), lane = tid & 63, wr = wid >> 2, wc = wid & 3, fr = lane & 15, fq = lane >> 4;
; __global__ void __launch_bounds__(512, 2) mega_fwd(KArgs a) {
;     extern __shared__ __attribute__((aligned(16))) unsigned char smem[];
;     cg::grid_group grid = cg::this_grid();
;     LAS unsigned char* lds = (LAS unsigned char*)smem;
;     const int G = gridDim.x, bx = blockIdx.x;
;     const float* x = (const float*)a.in[0];
;     grid.sync();
_Z8mega_fwd5KArgs:
	s_load_dwordx8 s[4:11], s[0:1], 0x80
	s_load_dwordx4 s[68:71], s[0:1], 0xa0
	s_load_dword s33, s[0:1], 0xb0
	v_and_b32_e32 v1, 0x3fffffff, v0
	s_mov_b32 s60, s2
	v_readfirstlane_b32 s61, v1
	s_bitcmp1_b32 s61, 8
	s_cbranch_scc0 .Lat_prio_lo
	s_setprio 1
.Lat_prio_lo:
	v_cmp_eq_u32_e32 vcc, 0, v1
	s_waitcnt lgkmcnt(0)
	v_writelane_b32 v253, s4, 0
	s_barrier
	s_nop 0
	v_writelane_b32 v253, s5, 1
	v_writelane_b32 v253, s6, 2
	v_writelane_b32 v253, s7, 3
	v_writelane_b32 v253, s8, 4
	v_writelane_b32 v253, s9, 5
	v_writelane_b32 v253, s10, 6
	v_writelane_b32 v253, s11, 7
	s_add_u32 s4, s0, 0xa8
	s_addc_u32 s5, s1, 0
	s_and_saveexec_b64 s[2:3], vcc
	s_cbranch_execz .LBB0_10
	buffer_wbl2 sc1
	s_load_dwordx2 s[4:5], s[4:5], 0x58
	s_mov_b64 s[6:7], exec
	v_mbcnt_lo_u32_b32 v1, s6, 0
	v_mbcnt_hi_u32_b32 v1, s7, v1
	v_cmp_eq_u32_e32 vcc, 0, v1
	s_waitcnt lgkmcnt(0)
	s_load_dword s10, s[4:5], 0x28
	s_and_saveexec_b64 s[8:9], vcc
	s_cbranch_execz .LBB0_3
	s_bcnt1_i32_b64 s6, s[6:7]
	v_mov_b32_e32 v2, 0
	v_mov_b32_e32 v3, s6
	global_atomic_add v2, v2, v3, s[4:5] offset:32 sc0

; #define PG8_STAGE(bufoff, gbase, voff) do { _Pragma("unroll") for (int _i = 0; _i < 2; ++_i) \
;         __builtin_amdgcn_global_load_lds((const unsigned*)((const char*)(gbase) + (voff)[_i]), (PG8_LAS unsigned*)(lds + (bufoff) + ldsw + _i * 8192), 16, 0, 0); } while (0)
; #define PG8_LDA(dst, b, h) do { _Pragma("unroll") for (int m = 0; m < 4; ++m) _Pragma("unroll") for (int k = 0; k < 2; ++k) dst[m][k] = *(const PG8_LAS bf16x8*)(lds + PG8_SA(b, h) + aoff + m * 2048 + k * 1024); } while (0)
; #define PG8_LDB(dst, b, h) do { _Pragma("unroll") for (int n = 0; n < 2; ++n) _Pragma("unroll") for (int k = 0; k < 2; ++k) dst[n][k] = *(const PG8_LAS bf16x8*)(lds + PG8_SB(b, h) + boff + n * 2048 + k * 1024); } while (0)
; #define PG8_MMA(ai, bj, At, Bt) do { __builtin_amdgcn_s_setprio(1); _Pragma("unroll") for (int m = 0; m < 4; ++m) _Pragma("unroll") for (int n = 0; n < 2; ++n) _Pragma("unroll") for (int k = 0; k < 2; ++k) \
;         acc[ai][bj][m][n] = __builtin_amdgcn_mfma_f32_16x16x32_bf16(Bt[n][k], At[m][k], acc[ai][bj][m][n], 0, 0, 0); __builtin_amdgcn_s_setprio(0); } while (0)
; #define PG8_WAIT_V(n) asm volatile("s_waitcnt vmcnt(" #n ")" ::: "memory")
; #define PG8_WAIT_L(n) asm volatile("s_waitcnt lgkmcnt(" #n ")" ::: "memory")
; #define PG8_BAR __builtin_amdgcn_s_barrier()
; template <class Epi, class Sched, bool ALIGN_EPI = false, bool SP2 = false>
; __device__ __forceinline__ void gemm_phase(PG8_LAS unsigned char* lds, const Gemm g, const Sched& S, const Epi& E) {
;     ...
;             const char* a1 = cA + (size_t)(t + 1) * kstep;
;             const char* a2 = last ? nA : cA + (size_t)(t + 2) * kstep; const char* b2 = last ? nB : cB + (size_t)(t + 2) * kstep;
;             const char* a3 = a2 + kstep; const char* b3 = b2 + kstep;
;             if (last && has_next) S.a_ready(nxt);
;             if constexpr (SP2) {
;             PG8_LDB(B0, 0, 0); PG8_LDB(B1, 0, 1); PG8_SCHED; PG8_LDA(At, 0, 0); PG8_STAGE(PG8_SA(1, 1), a1 + hstepA, voffA);
;             PG8_WAIT_V(8); PG8_WAIT_L(0); PG8_BAR; PG8_MMA(0, 0, At, B0); PG8_MMA(0, 1, At, B1); PG8_BAR; PG8_SCHED;
;             PG8_LDA(At, 0, 1); PG8_STAGE(PG8_SB(0, 0), b2, voffB); PG8_STAGE(PG8_SB(0, 1), b2 + hstepB, voffB); PG8_STAGE(PG8_SA(0, 0), a2, voffA);
;             PG8_WAIT_V(8); PG8_WAIT_L(0); PG8_BAR; PG8_MMA(1, 0, At, B0); PG8_MMA(1, 1, At, B1); PG8_BAR; PG8_SCHED;
.LBB0_201:
	s_add_u32 s28, s26, 0xfff80080
	s_addc_u32 s29, s27, -1
	s_add_i32 s49, 0, 0x10000
	s_cmp_eq_u32 s48, 28
	s_cselect_b32 s31, s21, s29
	s_cselect_b32 s30, s44, s28
	s_cselect_b32 s29, s19, s47
	s_cselect_b32 s28, s45, s46
	s_add_i32 s52, 0, 0x14000
	v_add_u32_e32 v156, s49, v145
	v_add_u32_e32 v172, s52, v145
	ds_read_b128 v[140:143], v156
	ds_read_b128 v[148:151], v156 offset:1024
	ds_read_b128 v[152:155], v156 offset:2048
	ds_read_b128 v[156:159], v156 offset:3072
	ds_read_b128 v[160:163], v172
	ds_read_b128 v[164:167], v172 offset:1024
	ds_read_b128 v[168:171], v172 offset:2048
	ds_read_b128 v[172:175], v172 offset:3072
	v_lshl_add_u64 v[192:193], s[26:27], 0, v[138:139]
	s_add_i32 m0, s35, 0xc000
	ds_read_b128 v[176:179], v147
	ds_read_b128 v[180:183], v147 offset:1024
	ds_read_b128 v[184:187], v147 offset:2048
	ds_read_b128 v[188:191], v147 offset:3072
	ds_read_b128 v[206:209], v147 offset:4096
	ds_read_b128 v[210:213], v147 offset:5120
	ds_read_b128 v[214:217], v147 offset:6144
	ds_read_b128 v[218:221], v147 offset:7168
	global_load_lds_dwordx4 v[192:193], off
	v_lshl_add_u64 v[192:193], s[26:27], 0, v[136:137]
	s_add_i32 m0, s35, 0xe000
	s_nop 0
	global_load_lds_dwordx4 v[192:193], off
	s_waitcnt vmcnt(8)
	s_waitcnt lgkmcnt(0)
	s_barrier
	s_waitcnt lgkmcnt(0)
	v_mfma_f32_16x16x32_bf16 v[126:129], v[140:143], v[176:179], v[126:129]
	v_mfma_f32_16x16x32_bf16 v[122:125], v[152:155], v[176:179], v[122:125]
	v_mfma_f32_16x16x32_bf16 v[108:111], v[140:143], v[184:187], v[108:111]
	v_mfma_f32_16x16x32_bf16 v[104:107], v[152:155], v[184:187], v[104:107]
	v_mfma_f32_16x16x32_bf16 v[92:95], v[140:143], v[206:209], v[92:95]
	v_mfma_f32_16x16x32_bf16 v[88:91], v[152:155], v[206:209], v[88:91]
	v_mfma_f32_16x16x32_bf16 v[76:79], v[140:143], v[214:217], v[76:79]
	v_mfma_f32_16x16x32_bf16 v[72:75], v[152:155], v[214:217], v[72:75]
	v_mfma_f32_16x16x32_bf16 v[126:129], v[148:151], v[180:183], v[126:129]
	v_mfma_f32_16x16x32_bf16 v[122:125], v[156:159], v[180:183], v[122:125]
	v_mfma_f32_16x16x32_bf16 v[108:111], v[148:151], v[188:191], v[108:111]
	v_mfma_f32_16x16x32_bf16 v[104:107], v[156:159], v[188:191], v[104:107]
	v_mfma_f32_16x16x32_bf16 v[92:95], v[148:151], v[210:213], v[92:95]
	v_mfma_f32_16x16x32_bf16 v[88:91], v[156:159], v[210:213], v[88:91]
	v_mfma_f32_16x16x32_bf16 v[76:79], v[148:151], v[218:221], v[76:79]
	v_mfma_f32_16x16x32_bf16 v[72:75], v[156:159], v[218:221], v[72:75]
	v_mfma_f32_16x16x32_bf16 v[118:121], v[160:163], v[176:179], v[118:121]
	v_mfma_f32_16x16x32_bf16 v[114:117], v[168:171], v[176:179], v[114:117]
	v_mfma_f32_16x16x32_bf16 v[100:103], v[160:163], v[184:187], v[100:103]
	v_mfma_f32_16x16x32_bf16 v[96:99], v[168:171], v[184:187], v[96:99]
	v_mfma_f32_16x16x32_bf16 v[84:87], v[160:163], v[206:209], v[84:87]
	v_mfma_f32_16x16x32_bf16 v[80:83], v[168:171], v[206:209], v[80:83]
	v_mfma_f32_16x16x32_bf16 v[68:71], v[160:163], v[214:217], v[68:71]
	v_mfma_f32_16x16x32_bf16 v[64:67], v[168:171], v[214:217], v[64:67]
	v_mfma_f32_16x16x32_bf16 v[118:121], v[164:167], v[180:183], v[118:121]
	v_mfma_f32_16x16x32_bf16 v[114:117], v[172:175], v[180:183], v[114:117]
	v_mfma_f32_16x16x32_bf16 v[100:103], v[164:167], v[188:191], v[100:103]
	v_mfma_f32_16x16x32_bf16 v[96:99], v[172:175], v[188:191], v[96:99]
	v_mfma_f32_16x16x32_bf16 v[84:87], v[164:167], v[210:213], v[84:87]
	v_mfma_f32_16x16x32_bf16 v[80:83], v[172:175], v[210:213], v[80:83]
	v_mfma_f32_16x16x32_bf16 v[68:71], v[164:167], v[218:221], v[68:71]
	v_mfma_f32_16x16x32_bf16 v[64:67], v[172:175], v[218:221], v[64:67]
	s_barrier
	s_add_i32 s49, s49, s34
	v_lshl_add_u64 v[192:193], s[28:29], 0, v[112:113]
	s_mov_b32 m0, s49
	ds_read_b128 v[176:179], v147 offset:16384
	ds_read_b128 v[180:183], v147 offset:17408
	ds_read_b128 v[184:187], v147 offset:18432
	ds_read_b128 v[188:191], v147 offset:19456
	ds_read_b128 v[206:209], v147 offset:20480
	ds_read_b128 v[210:213], v147 offset:21504
	ds_read_b128 v[214:217], v147 offset:22528
	ds_read_b128 v[218:221], v147 offset:23552
	global_load_lds_dwordx4 v[192:193], off
	s_add_i32 m0, s49, 0x2000
	s_add_u32 s50, s28, 0x80000
	v_lshl_add_u64 v[196:197], s[28:29], 0, v[130:131]
	s_addc_u32 s51, s29, 0
	s_add_i32 s49, s52, s34
	global_load_lds_dwordx4 v[196:197], off
	v_lshl_add_u64 v[198:199], s[50:51], 0, v[112:113]
	s_mov_b32 m0, s49
	v_lshl_add_u64 v[202:203], s[30:31], 0, v[132:133]
	global_load_lds_dwordx4 v[198:199], off
	v_lshl_add_u64 v[198:199], s[50:51], 0, v[130:131]
	s_add_i32 m0, s49, 0x2000
	s_nop 0
	global_load_lds_dwordx4 v[198:199], off
	v_lshl_add_u64 v[198:199], s[30:31], 0, v[134:135]
	s_mov_b32 m0, s35
	s_nop 0
	global_load_lds_dwordx4 v[198:199], off
	s_mov_b32 m0, s36
	s_nop 0
	global_load_lds_dwordx4 v[202:203], off
	s_waitcnt vmcnt(8)
	s_waitcnt lgkmcnt(0)
	s_barrier
; #define PG8_STAGE(bufoff, gbase, voff) do { _Pragma("unroll") for (int _i = 0; _i < 2; ++_i) \
;         __builtin_amdgcn_global_load_lds((const unsigned*)((const char*)(gbase) + (voff)[_i]), (PG8_LAS unsigned*)(lds + (bufoff) + ldsw + _i * 8192), 16, 0, 0); } while (0)
; #define PG8_LDA(dst, b, h) do { _Pragma("unroll") for (int m = 0; m < 4; ++m) _Pragma("unroll") for (int k = 0; k < 2; ++k) dst[m][k] = *(const PG8_LAS bf16x8*)(lds + PG8_SA(b, h) + aoff + m * 2048 + k * 1024); } while (0)
; #define PG8_LDB(dst, b, h) do { _Pragma("unroll") for (int n = 0; n < 2; ++n) _Pragma("unroll") for (int k = 0; k < 2; ++k) dst[n][k] = *(const PG8_LAS bf16x8*)(lds + PG8_SB(b, h) + boff + n * 2048 + k * 1024); } while (0)
; #define PG8_MMA(ai, bj, At, Bt) do { __builtin_amdgcn_s_setprio(1); _Pragma("unroll") for (int m = 0; m < 4; ++m) _Pragma("unroll") for (int n = 0; n < 2; ++n) _Pragma("unroll") for (int k = 0; k < 2; ++k) \
;         acc[ai][bj][m][n] = __builtin_amdgcn_mfma_f32_16x16x32_bf16(Bt[n][k], At[m][k], acc[ai][bj][m][n], 0, 0, 0); __builtin_amdgcn_s_setprio(0); } while (0)
; #define PG8_WAIT_V(n) asm volatile("s_waitcnt vmcnt(" #n ")" ::: "memory")
; #define PG8_WAIT_L(n) asm volatile("s_waitcnt lgkmcnt(" #n ")" ::: "memory")
; #define PG8_BAR __builtin_amdgcn_s_barrier()
; #define PG8_SCHED __builtin_amdgcn_sched_barrier(0)
; template <class Epi, class Sched, bool ALIGN_EPI = false, bool SP2 = false>
; __device__ __forceinline__ void gemm_phase(PG8_LAS unsigned char* lds, const Gemm g, const Sched& S, const Epi& E) {
;     ...
;             PG8_WAIT_V(8); PG8_WAIT_L(0); PG8_BAR; PG8_MMA(1, 0, At, B0); PG8_MMA(1, 1, At, B1); PG8_BAR; PG8_SCHED;
;             PG8_LDB(B0, 1, 0); PG8_LDB(B1, 1, 1); PG8_SCHED; PG8_LDA(At, 1, 0); PG8_STAGE(PG8_SA(0, 1), a2 + hstepA, voffA);
;             PG8_WAIT_V(8); PG8_WAIT_L(0); PG8_BAR; PG8_MMA(0, 0, At, B0); PG8_MMA(0, 1, At, B1); PG8_BAR; PG8_SCHED;
;             PG8_LDA(At, 1, 1); PG8_STAGE(PG8_SB(1, 0), b3, voffB); PG8_STAGE(PG8_SB(1, 1), b3 + hstepB, voffB); PG8_STAGE(PG8_SA(1, 0), a3, voffA);
	s_waitcnt lgkmcnt(0)
	v_mfma_f32_16x16x32_bf16 v[60:63], v[140:143], v[176:179], v[60:63]
	v_mfma_f32_16x16x32_bf16 v[56:59], v[152:155], v[176:179], v[56:59]
	v_mfma_f32_16x16x32_bf16 v[44:47], v[140:143], v[184:187], v[44:47]
	v_mfma_f32_16x16x32_bf16 v[40:43], v[152:155], v[184:187], v[40:43]
	v_mfma_f32_16x16x32_bf16 v[28:31], v[140:143], v[206:209], v[28:31]
	v_mfma_f32_16x16x32_bf16 v[24:27], v[152:155], v[206:209], v[24:27]
	v_mfma_f32_16x16x32_bf16 v[12:15], v[140:143], v[214:217], v[12:15]
	v_mfma_f32_16x16x32_bf16 v[8:11], v[152:155], v[214:217], v[8:11]
	v_mfma_f32_16x16x32_bf16 v[60:63], v[148:151], v[180:183], v[60:63]
	v_mfma_f32_16x16x32_bf16 v[56:59], v[156:159], v[180:183], v[56:59]
	v_mfma_f32_16x16x32_bf16 v[44:47], v[148:151], v[188:191], v[44:47]
	v_mfma_f32_16x16x32_bf16 v[40:43], v[156:159], v[188:191], v[40:43]
	v_mfma_f32_16x16x32_bf16 v[28:31], v[148:151], v[210:213], v[28:31]
	v_mfma_f32_16x16x32_bf16 v[24:27], v[156:159], v[210:213], v[24:27]
	v_mfma_f32_16x16x32_bf16 v[12:15], v[148:151], v[218:221], v[12:15]
	v_mfma_f32_16x16x32_bf16 v[8:11], v[156:159], v[218:221], v[8:11]
	v_mfma_f32_16x16x32_bf16 v[52:55], v[160:163], v[176:179], v[52:55]
	v_mfma_f32_16x16x32_bf16 v[48:51], v[168:171], v[176:179], v[48:51]
	v_mfma_f32_16x16x32_bf16 v[36:39], v[160:163], v[184:187], v[36:39]
	v_mfma_f32_16x16x32_bf16 v[32:35], v[168:171], v[184:187], v[32:35]
	v_mfma_f32_16x16x32_bf16 v[20:23], v[160:163], v[206:209], v[20:23]
	v_mfma_f32_16x16x32_bf16 v[16:19], v[168:171], v[206:209], v[16:19]
	v_mfma_f32_16x16x32_bf16 v[4:7], v[160:163], v[214:217], v[4:7]
	v_mfma_f32_16x16x32_bf16 v[0:3], v[168:171], v[214:217], v[0:3]
	v_mfma_f32_16x16x32_bf16 v[52:55], v[164:167], v[180:183], v[52:55]
	v_mfma_f32_16x16x32_bf16 v[48:51], v[172:175], v[180:183], v[48:51]
	v_mfma_f32_16x16x32_bf16 v[36:39], v[164:167], v[188:191], v[36:39]
	v_mfma_f32_16x16x32_bf16 v[32:35], v[172:175], v[188:191], v[32:35]
	v_mfma_f32_16x16x32_bf16 v[20:23], v[164:167], v[210:213], v[20:23]
	v_mfma_f32_16x16x32_bf16 v[16:19], v[172:175], v[210:213], v[16:19]
	v_mfma_f32_16x16x32_bf16 v[4:7], v[164:167], v[218:221], v[4:7]
	v_mfma_f32_16x16x32_bf16 v[0:3], v[172:175], v[218:221], v[0:3]
	s_barrier
	s_add_i32 s49, 0, 0x18000
	s_add_i32 s50, 0, 0x1c000
	v_add_u32_e32 v156, s49, v145
	v_add_u32_e32 v172, s50, v145
	ds_read_b128 v[140:143], v156
	ds_read_b128 v[148:151], v156 offset:1024
	ds_read_b128 v[152:155], v156 offset:2048
	ds_read_b128 v[156:159], v156 offset:3072
	ds_read_b128 v[160:163], v172
	ds_read_b128 v[164:167], v172 offset:1024
	ds_read_b128 v[168:171], v172 offset:2048
	ds_read_b128 v[172:175], v172 offset:3072
	s_add_u32 s30, s30, 0x80000
	s_addc_u32 s31, s31, 0
	s_mov_b32 m0, s37
	v_lshl_add_u64 v[204:205], s[30:31], 0, v[134:135]
	ds_read_b128 v[176:179], v147 offset:32768
	ds_read_b128 v[180:183], v147 offset:33792
	ds_read_b128 v[184:187], v147 offset:34816
	ds_read_b128 v[188:191], v147 offset:35840
	ds_read_b128 v[206:209], v147 offset:36864
	ds_read_b128 v[210:213], v147 offset:37888
	ds_read_b128 v[214:217], v147 offset:38912
	ds_read_b128 v[218:221], v147 offset:39936
	global_load_lds_dwordx4 v[204:205], off
	v_lshl_add_u64 v[204:205], s[30:31], 0, v[132:133]
	s_mov_b32 m0, s38
	s_nop 0
	global_load_lds_dwordx4 v[204:205], off
	s_waitcnt vmcnt(8)
	s_waitcnt lgkmcnt(0)
	s_barrier
	s_waitcnt lgkmcnt(0)
	v_mfma_f32_16x16x32_bf16 v[126:129], v[140:143], v[176:179], v[126:129]
	v_mfma_f32_16x16x32_bf16 v[122:125], v[152:155], v[176:179], v[122:125]
	v_mfma_f32_16x16x32_bf16 v[108:111], v[140:143], v[184:187], v[108:111]
	v_mfma_f32_16x16x32_bf16 v[104:107], v[152:155], v[184:187], v[104:107]
	v_mfma_f32_16x16x32_bf16 v[92:95], v[140:143], v[206:209], v[92:95]
	v_mfma_f32_16x16x32_bf16 v[88:91], v[152:155], v[206:209], v[88:91]
	v_mfma_f32_16x16x32_bf16 v[76:79], v[140:143], v[214:217], v[76:79]
	v_mfma_f32_16x16x32_bf16 v[72:75], v[152:155], v[214:217], v[72:75]
	v_mfma_f32_16x16x32_bf16 v[126:129], v[148:151], v[180:183], v[126:129]
	v_mfma_f32_16x16x32_bf16 v[122:125], v[156:159], v[180:183], v[122:125]
	v_mfma_f32_16x16x32_bf16 v[108:111], v[148:151], v[188:191], v[108:111]
	v_mfma_f32_16x16x32_bf16 v[104:107], v[156:159], v[188:191], v[104:107]
	v_mfma_f32_16x16x32_bf16 v[92:95], v[148:151], v[210:213], v[92:95]
	v_mfma_f32_16x16x32_bf16 v[88:91], v[156:159], v[210:213], v[88:91]
	v_mfma_f32_16x16x32_bf16 v[76:79], v[148:151], v[218:221], v[76:79]
	v_mfma_f32_16x16x32_bf16 v[72:75], v[156:159], v[218:221], v[72:75]
	v_mfma_f32_16x16x32_bf16 v[118:121], v[160:163], v[176:179], v[118:121]
	v_mfma_f32_16x16x32_bf16 v[114:117], v[168:171], v[176:179], v[114:117]
	v_mfma_f32_16x16x32_bf16 v[100:103], v[160:163], v[184:187], v[100:103]
	v_mfma_f32_16x16x32_bf16 v[96:99], v[168:171], v[184:187], v[96:99]
	v_mfma_f32_16x16x32_bf16 v[84:87], v[160:163], v[206:209], v[84:87]
	v_mfma_f32_16x16x32_bf16 v[80:83], v[168:171], v[206:209], v[80:83]
	v_mfma_f32_16x16x32_bf16 v[68:71], v[160:163], v[214:217], v[68:71]
	v_mfma_f32_16x16x32_bf16 v[64:67], v[168:171], v[214:217], v[64:67]
	v_mfma_f32_16x16x32_bf16 v[118:121], v[164:167], v[180:183], v[118:121]
	v_mfma_f32_16x16x32_bf16 v[114:117], v[172:175], v[180:183], v[114:117]
	v_mfma_f32_16x16x32_bf16 v[100:103], v[164:167], v[188:191], v[100:103]
	v_mfma_f32_16x16x32_bf16 v[96:99], v[172:175], v[188:191], v[96:99]
	v_mfma_f32_16x16x32_bf16 v[84:87], v[164:167], v[210:213], v[84:87]
	v_mfma_f32_16x16x32_bf16 v[80:83], v[172:175], v[210:213], v[80:83]
	v_mfma_f32_16x16x32_bf16 v[68:71], v[164:167], v[218:221], v[68:71]
	v_mfma_f32_16x16x32_bf16 v[64:67], v[172:175], v[218:221], v[64:67]
	s_barrier
; #define PG8_STAGE(bufoff, gbase, voff) do { _Pragma("unroll") for (int _i = 0; _i < 2; ++_i) \
;         __builtin_amdgcn_global_load_lds((const unsigned*)((const char*)(gbase) + (voff)[_i]), (PG8_LAS unsigned*)(lds + (bufoff) + ldsw + _i * 8192), 16, 0, 0); } while (0)
; #define PG8_LDA(dst, b, h) do { _Pragma("unroll") for (int m = 0; m < 4; ++m) _Pragma("unroll") for (int k = 0; k < 2; ++k) dst[m][k] = *(const PG8_LAS bf16x8*)(lds + PG8_SA(b, h) + aoff + m * 2048 + k * 1024); } while (0)
; #define PG8_MMA(ai, bj, At, Bt) do { __builtin_amdgcn_s_setprio(1); _Pragma("unroll") for (int m = 0; m < 4; ++m) _Pragma("unroll") for (int n = 0; n < 2; ++n) _Pragma("unroll") for (int k = 0; k < 2; ++k) \
;         acc[ai][bj][m][n] = __builtin_amdgcn_mfma_f32_16x16x32_bf16(Bt[n][k], At[m][k], acc[ai][bj][m][n], 0, 0, 0); __builtin_amdgcn_s_setprio(0); } while (0)
; #define PG8_WAIT_V(n) asm volatile("s_waitcnt vmcnt(" #n ")" ::: "memory")
; #define PG8_WAIT_L(n) asm volatile("s_waitcnt lgkmcnt(" #n ")" ::: "memory")
; #define PG8_BAR __builtin_amdgcn_s_barrier()
; #define PG8_SCHED __builtin_amdgcn_sched_barrier(0)
; template <class Epi, class Sched, bool ALIGN_EPI = false, bool SP2 = false>
; __device__ __forceinline__ void gemm_phase(PG8_LAS unsigned char* lds, const Gemm g, const Sched& S, const Epi& E) {
;     ...
;             PG8_LDA(At, 1, 1); PG8_STAGE(PG8_SB(1, 0), b3, voffB); PG8_STAGE(PG8_SB(1, 1), b3 + hstepB, voffB); PG8_STAGE(PG8_SA(1, 0), a3, voffA);
;             PG8_WAIT_V(8); PG8_WAIT_L(0); PG8_BAR; PG8_MMA(1, 0, At, B0); PG8_MMA(1, 1, At, B1); PG8_BAR; PG8_SCHED;
	s_add_i32 s30, s49, s34
	v_lshl_add_u64 v[192:193], v[192:193], 0, s[2:3]
	s_mov_b32 m0, s30
	ds_read_b128 v[176:179], v147 offset:49152
	ds_read_b128 v[180:183], v147 offset:50176
	ds_read_b128 v[184:187], v147 offset:51200
	ds_read_b128 v[188:191], v147 offset:52224
	ds_read_b128 v[206:209], v147 offset:53248
	ds_read_b128 v[210:213], v147 offset:54272
	ds_read_b128 v[214:217], v147 offset:55296
	ds_read_b128 v[218:221], v147 offset:56320
	global_load_lds_dwordx4 v[192:193], off
	s_add_i32 m0, s30, 0x2000
	s_add_u32 s28, s28, 0x80080
	v_lshl_add_u64 v[192:193], v[196:197], 0, s[2:3]
	s_addc_u32 s29, s29, 0
	s_add_i32 s30, s50, s34
	global_load_lds_dwordx4 v[192:193], off
	v_lshl_add_u64 v[192:193], s[28:29], 0, v[112:113]
	s_mov_b32 m0, s30
	s_nop 0
	global_load_lds_dwordx4 v[192:193], off
	v_lshl_add_u64 v[192:193], s[28:29], 0, v[130:131]
	s_add_i32 m0, s30, 0x2000
	s_nop 0
	global_load_lds_dwordx4 v[192:193], off
	v_lshl_add_u64 v[192:193], v[198:199], 0, s[2:3]
	s_mov_b32 m0, s39
	s_nop 0
	global_load_lds_dwordx4 v[192:193], off
	v_lshl_add_u64 v[192:193], v[202:203], 0, s[2:3]
	s_mov_b32 m0, s40
	s_nop 0
	global_load_lds_dwordx4 v[192:193], off
	s_waitcnt vmcnt(8)
	s_waitcnt lgkmcnt(0)
	s_barrier
	s_waitcnt lgkmcnt(0)
	v_mfma_f32_16x16x32_bf16 v[60:63], v[140:143], v[176:179], v[60:63]
	v_mfma_f32_16x16x32_bf16 v[56:59], v[152:155], v[176:179], v[56:59]
	v_mfma_f32_16x16x32_bf16 v[44:47], v[140:143], v[184:187], v[44:47]
	v_mfma_f32_16x16x32_bf16 v[40:43], v[152:155], v[184:187], v[40:43]
	v_mfma_f32_16x16x32_bf16 v[28:31], v[140:143], v[206:209], v[28:31]
	v_mfma_f32_16x16x32_bf16 v[24:27], v[152:155], v[206:209], v[24:27]
	v_mfma_f32_16x16x32_bf16 v[12:15], v[140:143], v[214:217], v[12:15]
	v_mfma_f32_16x16x32_bf16 v[8:11], v[152:155], v[214:217], v[8:11]
	v_mfma_f32_16x16x32_bf16 v[60:63], v[148:151], v[180:183], v[60:63]
	v_mfma_f32_16x16x32_bf16 v[56:59], v[156:159], v[180:183], v[56:59]
	v_mfma_f32_16x16x32_bf16 v[44:47], v[148:151], v[188:191], v[44:47]
	v_mfma_f32_16x16x32_bf16 v[40:43], v[156:159], v[188:191], v[40:43]
	v_mfma_f32_16x16x32_bf16 v[28:31], v[148:151], v[210:213], v[28:31]
	v_mfma_f32_16x16x32_bf16 v[24:27], v[156:159], v[210:213], v[24:27]
	v_mfma_f32_16x16x32_bf16 v[12:15], v[148:151], v[218:221], v[12:15]
	v_mfma_f32_16x16x32_bf16 v[8:11], v[156:159], v[218:221], v[8:11]
	v_mfma_f32_16x16x32_bf16 v[52:55], v[160:163], v[176:179], v[52:55]
	v_mfma_f32_16x16x32_bf16 v[48:51], v[168:171], v[176:179], v[48:51]
	v_mfma_f32_16x16x32_bf16 v[36:39], v[160:163], v[184:187], v[36:39]
	v_mfma_f32_16x16x32_bf16 v[32:35], v[168:171], v[184:187], v[32:35]
	v_mfma_f32_16x16x32_bf16 v[20:23], v[160:163], v[206:209], v[20:23]
	v_mfma_f32_16x16x32_bf16 v[16:19], v[168:171], v[206:209], v[16:19]
	v_mfma_f32_16x16x32_bf16 v[4:7], v[160:163], v[214:217], v[4:7]
	v_mfma_f32_16x16x32_bf16 v[0:3], v[168:171], v[214:217], v[0:3]
	v_mfma_f32_16x16x32_bf16 v[52:55], v[164:167], v[180:183], v[52:55]
	v_mfma_f32_16x16x32_bf16 v[48:51], v[172:175], v[180:183], v[48:51]
	v_mfma_f32_16x16x32_bf16 v[36:39], v[164:167], v[188:191], v[36:39]
	v_mfma_f32_16x16x32_bf16 v[32:35], v[172:175], v[188:191], v[32:35]
	v_mfma_f32_16x16x32_bf16 v[20:23], v[164:167], v[210:213], v[20:23]
	v_mfma_f32_16x16x32_bf16 v[16:19], v[172:175], v[210:213], v[16:19]
	v_mfma_f32_16x16x32_bf16 v[4:7], v[164:167], v[218:221], v[4:7]
	v_mfma_f32_16x16x32_bf16 v[0:3], v[172:175], v[218:221], v[0:3]
	s_barrier
	s_add_i32 s48, s48, 2
	s_add_u32 s46, s46, 0x100
	s_addc_u32 s47, s47, 0
	s_add_u32 s26, s26, 0x100
	s_addc_u32 s27, s27, 0
	s_cmp_gt_u32 s48, 29
	s_cbranch_scc0 .LBB0_201
	s_and_b64 vcc, exec, s[16:17]
	s_cbranch_vccz .LBB0_204
	s_barrier

; #define PG8_STAGE(bufoff, gbase, voff) do { _Pragma("unroll") for (int _i = 0; _i < 2; ++_i) \
;         __builtin_amdgcn_global_load_lds((const unsigned*)((const char*)(gbase) + (voff)[_i]), (PG8_LAS unsigned*)(lds + (bufoff) + ldsw + _i * 8192), 16, 0, 0); } while (0)
; #define PG8_LDA(dst, b, h) do { _Pragma("unroll") for (int m = 0; m < 4; ++m) _Pragma("unroll") for (int k = 0; k < 2; ++k) dst[m][k] = *(const PG8_LAS bf16x8*)(lds + PG8_SA(b, h) + aoff + m * 2048 + k * 1024); } while (0)
; #define PG8_LDB(dst, b, h) do { _Pragma("unroll") for (int n = 0; n < 2; ++n) _Pragma("unroll") for (int k = 0; k < 2; ++k) dst[n][k] = *(const PG8_LAS bf16x8*)(lds + PG8_SB(b, h) + boff + n * 2048 + k * 1024); } while (0)
; #define PG8_MMA(ai, bj, At, Bt) do { __builtin_amdgcn_s_setprio(1); _Pragma("unroll") for (int m = 0; m < 4; ++m) _Pragma("unroll") for (int n = 0; n < 2; ++n) _Pragma("unroll") for (int k = 0; k < 2; ++k) \
;         acc[ai][bj][m][n] = __builtin_amdgcn_mfma_f32_16x16x32_bf16(Bt[n][k], At[m][k], acc[ai][bj][m][n], 0, 0, 0); __builtin_amdgcn_s_setprio(0); } while (0)
; #define PG8_WAIT_V(n) asm volatile("s_waitcnt vmcnt(" #n ")" ::: "memory")
; #define PG8_WAIT_L(n) asm volatile("s_waitcnt lgkmcnt(" #n ")" ::: "memory")
; #define PG8_BAR __builtin_amdgcn_s_barrier()
; template <class Epi, class Sched, bool ALIGN_EPI = false, bool SP2 = false>
; __device__ __forceinline__ void gemm_phase(PG8_LAS unsigned char* lds, const Gemm g, const Sched& S, const Epi& E) {
;     ...
;             const char* a1 = cA + (size_t)(t + 1) * kstep;
;             const char* a2 = last ? nA : cA + (size_t)(t + 2) * kstep; const char* b2 = last ? nB : cB + (size_t)(t + 2) * kstep;
;             const char* a3 = a2 + kstep; const char* b3 = b2 + kstep;
;             if (last && has_next) S.a_ready(nxt);
;             if constexpr (SP2) {
;             PG8_LDB(B0, 0, 0); PG8_LDB(B1, 0, 1); PG8_SCHED; PG8_LDA(At, 0, 0); PG8_STAGE(PG8_SA(1, 1), a1 + hstepA, voffA);
;             PG8_WAIT_V(8); PG8_WAIT_L(0); PG8_BAR; PG8_MMA(0, 0, At, B0); PG8_MMA(0, 1, At, B1); PG8_BAR; PG8_SCHED;
;             PG8_LDA(At, 0, 1); PG8_STAGE(PG8_SB(0, 0), b2, voffB); PG8_STAGE(PG8_SB(0, 1), b2 + hstepB, voffB); PG8_STAGE(PG8_SA(0, 0), a2, voffA);
;             PG8_WAIT_V(8); PG8_WAIT_L(0); PG8_BAR; PG8_MMA(1, 0, At, B0); PG8_MMA(1, 1, At, B1); PG8_BAR; PG8_SCHED;
.LBB0_356:
	s_add_u32 s6, s24, 0x100
	s_addc_u32 s7, s25, 0
	s_add_i32 s51, 0, 0x10000
	s_cmp_eq_u32 s50, 4
	s_cselect_b32 s29, s21, s7
	s_cselect_b32 s28, s20, s6
	s_cselect_b32 s27, s19, s49
	s_cselect_b32 s26, s47, s48
	s_add_i32 s52, 0, 0x14000
	v_add_u32_e32 v142, s51, v229
	v_add_u32_e32 v158, s52, v229
	ds_read_b128 v[122:125], v142
	ds_read_b128 v[126:129], v142 offset:1024
	ds_read_b128 v[138:141], v142 offset:2048
	ds_read_b128 v[142:145], v142 offset:3072
	ds_read_b128 v[146:149], v158
	ds_read_b128 v[150:153], v158 offset:1024
	ds_read_b128 v[154:157], v158 offset:2048
	ds_read_b128 v[158:161], v158 offset:3072
	v_lshl_add_u64 v[196:197], s[24:25], 0, v[206:207]
	s_add_i32 m0, s37, 0xc000
	ds_read_b128 v[162:165], v231
	ds_read_b128 v[166:169], v231 offset:1024
	ds_read_b128 v[170:173], v231 offset:2048
	ds_read_b128 v[174:177], v231 offset:3072
	ds_read_b128 v[178:181], v231 offset:4096
	ds_read_b128 v[182:185], v231 offset:5120
	ds_read_b128 v[208:211], v231 offset:6144
	ds_read_b128 v[212:215], v231 offset:7168
	global_load_lds_dwordx4 v[196:197], off
	v_lshl_add_u64 v[196:197], s[24:25], 0, v[192:193]
	s_add_i32 m0, s37, 0xe000
	s_nop 0
	global_load_lds_dwordx4 v[196:197], off
	s_waitcnt vmcnt(8)
	s_waitcnt lgkmcnt(0)
	s_barrier
	s_waitcnt lgkmcnt(0)
	v_mfma_f32_16x16x32_bf16 v[134:137], v[122:125], v[162:165], v[134:137]
	v_mfma_f32_16x16x32_bf16 v[130:133], v[138:141], v[162:165], v[130:133]
	v_mfma_f32_16x16x32_bf16 v[108:111], v[122:125], v[170:173], v[108:111]
	v_mfma_f32_16x16x32_bf16 v[104:107], v[138:141], v[170:173], v[104:107]
	v_mfma_f32_16x16x32_bf16 v[92:95], v[122:125], v[178:181], v[92:95]
	v_mfma_f32_16x16x32_bf16 v[88:91], v[138:141], v[178:181], v[88:91]
	v_mfma_f32_16x16x32_bf16 v[76:79], v[122:125], v[208:211], v[76:79]
	v_mfma_f32_16x16x32_bf16 v[72:75], v[138:141], v[208:211], v[72:75]
	v_mfma_f32_16x16x32_bf16 v[134:137], v[126:129], v[166:169], v[134:137]
	v_mfma_f32_16x16x32_bf16 v[130:133], v[142:145], v[166:169], v[130:133]
	v_mfma_f32_16x16x32_bf16 v[108:111], v[126:129], v[174:177], v[108:111]
	v_mfma_f32_16x16x32_bf16 v[104:107], v[142:145], v[174:177], v[104:107]
	v_mfma_f32_16x16x32_bf16 v[92:95], v[126:129], v[182:185], v[92:95]
	v_mfma_f32_16x16x32_bf16 v[88:91], v[142:145], v[182:185], v[88:91]
	v_mfma_f32_16x16x32_bf16 v[76:79], v[126:129], v[212:215], v[76:79]
	v_mfma_f32_16x16x32_bf16 v[72:75], v[142:145], v[212:215], v[72:75]
	v_mfma_f32_16x16x32_bf16 v[118:121], v[146:149], v[162:165], v[118:121]
	v_mfma_f32_16x16x32_bf16 v[114:117], v[154:157], v[162:165], v[114:117]
	v_mfma_f32_16x16x32_bf16 v[100:103], v[146:149], v[170:173], v[100:103]
	v_mfma_f32_16x16x32_bf16 v[96:99], v[154:157], v[170:173], v[96:99]
	v_mfma_f32_16x16x32_bf16 v[84:87], v[146:149], v[178:181], v[84:87]
	v_mfma_f32_16x16x32_bf16 v[80:83], v[154:157], v[178:181], v[80:83]
	v_mfma_f32_16x16x32_bf16 v[68:71], v[146:149], v[208:211], v[68:71]
	v_mfma_f32_16x16x32_bf16 v[64:67], v[154:157], v[208:211], v[64:67]
	v_mfma_f32_16x16x32_bf16 v[118:121], v[150:153], v[166:169], v[118:121]
	v_mfma_f32_16x16x32_bf16 v[114:117], v[158:161], v[166:169], v[114:117]
	v_mfma_f32_16x16x32_bf16 v[100:103], v[150:153], v[174:177], v[100:103]
	v_mfma_f32_16x16x32_bf16 v[96:99], v[158:161], v[174:177], v[96:99]
	v_mfma_f32_16x16x32_bf16 v[84:87], v[150:153], v[182:185], v[84:87]
	v_mfma_f32_16x16x32_bf16 v[80:83], v[158:161], v[182:185], v[80:83]
	v_mfma_f32_16x16x32_bf16 v[68:71], v[150:153], v[212:215], v[68:71]
	v_mfma_f32_16x16x32_bf16 v[64:67], v[158:161], v[212:215], v[64:67]
	s_barrier
	s_add_i32 s24, s51, s36
	v_lshl_add_u64 v[196:197], s[26:27], 0, v[112:113]
	s_mov_b32 m0, s24
	ds_read_b128 v[162:165], v231 offset:16384
	ds_read_b128 v[166:169], v231 offset:17408
	ds_read_b128 v[170:173], v231 offset:18432
	ds_read_b128 v[174:177], v231 offset:19456
	ds_read_b128 v[178:181], v231 offset:20480
	ds_read_b128 v[182:185], v231 offset:21504
	ds_read_b128 v[208:211], v231 offset:22528
	ds_read_b128 v[212:215], v231 offset:23552
	global_load_lds_dwordx4 v[196:197], off
	s_add_i32 m0, s24, 0x2000
	s_add_u32 s24, s26, 0x20000
	v_lshl_add_u64 v[198:199], s[26:27], 0, v[186:187]
	s_addc_u32 s25, s27, 0
	s_add_i32 s51, s52, s36
	global_load_lds_dwordx4 v[198:199], off
	v_lshl_add_u64 v[202:203], s[24:25], 0, v[112:113]
	s_mov_b32 m0, s51
	v_lshl_add_u64 v[204:205], s[28:29], 0, v[188:189]
	global_load_lds_dwordx4 v[202:203], off
	v_lshl_add_u64 v[202:203], s[24:25], 0, v[186:187]
	s_add_i32 m0, s51, 0x2000
	s_nop 0
	global_load_lds_dwordx4 v[202:203], off
	v_lshl_add_u64 v[202:203], s[28:29], 0, v[190:191]
	s_mov_b32 m0, s37
	s_nop 0
	global_load_lds_dwordx4 v[202:203], off
	s_mov_b32 m0, s38
	s_nop 0
	global_load_lds_dwordx4 v[204:205], off
	s_waitcnt vmcnt(8)
	s_waitcnt lgkmcnt(0)
	s_barrier
; #define PG8_STAGE(bufoff, gbase, voff) do { _Pragma("unroll") for (int _i = 0; _i < 2; ++_i) \
;         __builtin_amdgcn_global_load_lds((const unsigned*)((const char*)(gbase) + (voff)[_i]), (PG8_LAS unsigned*)(lds + (bufoff) + ldsw + _i * 8192), 16, 0, 0); } while (0)
; #define PG8_LDA(dst, b, h) do { _Pragma("unroll") for (int m = 0; m < 4; ++m) _Pragma("unroll") for (int k = 0; k < 2; ++k) dst[m][k] = *(const PG8_LAS bf16x8*)(lds + PG8_SA(b, h) + aoff + m * 2048 + k * 1024); } while (0)
; #define PG8_LDB(dst, b, h) do { _Pragma("unroll") for (int n = 0; n < 2; ++n) _Pragma("unroll") for (int k = 0; k < 2; ++k) dst[n][k] = *(const PG8_LAS bf16x8*)(lds + PG8_SB(b, h) + boff + n * 2048 + k * 1024); } while (0)
; #define PG8_MMA(ai, bj, At, Bt) do { __builtin_amdgcn_s_setprio(1); _Pragma("unroll") for (int m = 0; m < 4; ++m) _Pragma("unroll") for (int n = 0; n < 2; ++n) _Pragma("unroll") for (int k = 0; k < 2; ++k) \
;         acc[ai][bj][m][n] = __builtin_amdgcn_mfma_f32_16x16x32_bf16(Bt[n][k], At[m][k], acc[ai][bj][m][n], 0, 0, 0); __builtin_amdgcn_s_setprio(0); } while (0)
; #define PG8_WAIT_V(n) asm volatile("s_waitcnt vmcnt(" #n ")" ::: "memory")
; #define PG8_WAIT_L(n) asm volatile("s_waitcnt lgkmcnt(" #n ")" ::: "memory")
; #define PG8_BAR __builtin_amdgcn_s_barrier()
; #define PG8_SCHED __builtin_amdgcn_sched_barrier(0)
; template <class Epi, class Sched, bool ALIGN_EPI = false, bool SP2 = false>
; __device__ __forceinline__ void gemm_phase(PG8_LAS unsigned char* lds, const Gemm g, const Sched& S, const Epi& E) {
;     ...
;             PG8_WAIT_V(8); PG8_WAIT_L(0); PG8_BAR; PG8_MMA(1, 0, At, B0); PG8_MMA(1, 1, At, B1); PG8_BAR; PG8_SCHED;
;             PG8_LDB(B0, 1, 0); PG8_LDB(B1, 1, 1); PG8_SCHED; PG8_LDA(At, 1, 0); PG8_STAGE(PG8_SA(0, 1), a2 + hstepA, voffA);
;             PG8_WAIT_V(8); PG8_WAIT_L(0); PG8_BAR; PG8_MMA(0, 0, At, B0); PG8_MMA(0, 1, At, B1); PG8_BAR; PG8_SCHED;
;             PG8_LDA(At, 1, 1); PG8_STAGE(PG8_SB(1, 0), b3, voffB); PG8_STAGE(PG8_SB(1, 1), b3 + hstepB, voffB); PG8_STAGE(PG8_SA(1, 0), a3, voffA);
	s_waitcnt lgkmcnt(0)
	v_mfma_f32_16x16x32_bf16 v[60:63], v[122:125], v[162:165], v[60:63]
	v_mfma_f32_16x16x32_bf16 v[56:59], v[138:141], v[162:165], v[56:59]
	v_mfma_f32_16x16x32_bf16 v[44:47], v[122:125], v[170:173], v[44:47]
	v_mfma_f32_16x16x32_bf16 v[40:43], v[138:141], v[170:173], v[40:43]
	v_mfma_f32_16x16x32_bf16 v[28:31], v[122:125], v[178:181], v[28:31]
	v_mfma_f32_16x16x32_bf16 v[24:27], v[138:141], v[178:181], v[24:27]
	v_mfma_f32_16x16x32_bf16 v[12:15], v[122:125], v[208:211], v[12:15]
	v_mfma_f32_16x16x32_bf16 v[8:11], v[138:141], v[208:211], v[8:11]
	v_mfma_f32_16x16x32_bf16 v[60:63], v[126:129], v[166:169], v[60:63]
	v_mfma_f32_16x16x32_bf16 v[56:59], v[142:145], v[166:169], v[56:59]
	v_mfma_f32_16x16x32_bf16 v[44:47], v[126:129], v[174:177], v[44:47]
	v_mfma_f32_16x16x32_bf16 v[40:43], v[142:145], v[174:177], v[40:43]
	v_mfma_f32_16x16x32_bf16 v[28:31], v[126:129], v[182:185], v[28:31]
	v_mfma_f32_16x16x32_bf16 v[24:27], v[142:145], v[182:185], v[24:27]
	v_mfma_f32_16x16x32_bf16 v[12:15], v[126:129], v[212:215], v[12:15]
	v_mfma_f32_16x16x32_bf16 v[8:11], v[142:145], v[212:215], v[8:11]
	v_mfma_f32_16x16x32_bf16 v[52:55], v[146:149], v[162:165], v[52:55]
	v_mfma_f32_16x16x32_bf16 v[48:51], v[154:157], v[162:165], v[48:51]
	v_mfma_f32_16x16x32_bf16 v[36:39], v[146:149], v[170:173], v[36:39]
	v_mfma_f32_16x16x32_bf16 v[32:35], v[154:157], v[170:173], v[32:35]
	v_mfma_f32_16x16x32_bf16 v[20:23], v[146:149], v[178:181], v[20:23]
	v_mfma_f32_16x16x32_bf16 v[16:19], v[154:157], v[178:181], v[16:19]
	v_mfma_f32_16x16x32_bf16 v[4:7], v[146:149], v[208:211], v[4:7]
	v_mfma_f32_16x16x32_bf16 v[0:3], v[154:157], v[208:211], v[0:3]
	v_mfma_f32_16x16x32_bf16 v[52:55], v[150:153], v[166:169], v[52:55]
	v_mfma_f32_16x16x32_bf16 v[48:51], v[158:161], v[166:169], v[48:51]
	v_mfma_f32_16x16x32_bf16 v[36:39], v[150:153], v[174:177], v[36:39]
	v_mfma_f32_16x16x32_bf16 v[32:35], v[158:161], v[174:177], v[32:35]
	v_mfma_f32_16x16x32_bf16 v[20:23], v[150:153], v[182:185], v[20:23]
	v_mfma_f32_16x16x32_bf16 v[16:19], v[158:161], v[182:185], v[16:19]
	v_mfma_f32_16x16x32_bf16 v[4:7], v[150:153], v[212:215], v[4:7]
	v_mfma_f32_16x16x32_bf16 v[0:3], v[158:161], v[212:215], v[0:3]
	s_barrier
	s_add_i32 s51, 0, 0x18000
	s_add_i32 s52, 0, 0x1c000
	v_add_u32_e32 v142, s51, v229
	v_add_u32_e32 v158, s52, v229
	ds_read_b128 v[122:125], v142
	ds_read_b128 v[126:129], v142 offset:1024
	ds_read_b128 v[138:141], v142 offset:2048
	ds_read_b128 v[142:145], v142 offset:3072
	ds_read_b128 v[146:149], v158
	ds_read_b128 v[150:153], v158 offset:1024
	ds_read_b128 v[154:157], v158 offset:2048
	ds_read_b128 v[158:161], v158 offset:3072
	s_add_u32 s24, s28, 0x150000
	s_addc_u32 s25, s29, 0
	s_mov_b32 m0, s39
	v_lshl_add_u64 v[216:217], s[24:25], 0, v[190:191]
	ds_read_b128 v[162:165], v231 offset:32768
	ds_read_b128 v[166:169], v231 offset:33792
	ds_read_b128 v[170:173], v231 offset:34816
	ds_read_b128 v[174:177], v231 offset:35840
	ds_read_b128 v[178:181], v231 offset:36864
	ds_read_b128 v[182:185], v231 offset:37888
	ds_read_b128 v[208:211], v231 offset:38912
	ds_read_b128 v[212:215], v231 offset:39936
	global_load_lds_dwordx4 v[216:217], off
	v_lshl_add_u64 v[216:217], s[24:25], 0, v[188:189]
	s_mov_b32 m0, s40
	s_nop 0
	global_load_lds_dwordx4 v[216:217], off
	s_waitcnt vmcnt(8)
	s_waitcnt lgkmcnt(0)
	s_barrier
	s_waitcnt lgkmcnt(0)
	v_mfma_f32_16x16x32_bf16 v[134:137], v[122:125], v[162:165], v[134:137]
	v_mfma_f32_16x16x32_bf16 v[130:133], v[138:141], v[162:165], v[130:133]
	v_mfma_f32_16x16x32_bf16 v[108:111], v[122:125], v[170:173], v[108:111]
	v_mfma_f32_16x16x32_bf16 v[104:107], v[138:141], v[170:173], v[104:107]
	v_mfma_f32_16x16x32_bf16 v[92:95], v[122:125], v[178:181], v[92:95]
	v_mfma_f32_16x16x32_bf16 v[88:91], v[138:141], v[178:181], v[88:91]
	v_mfma_f32_16x16x32_bf16 v[76:79], v[122:125], v[208:211], v[76:79]
	v_mfma_f32_16x16x32_bf16 v[72:75], v[138:141], v[208:211], v[72:75]
	v_mfma_f32_16x16x32_bf16 v[134:137], v[126:129], v[166:169], v[134:137]
	v_mfma_f32_16x16x32_bf16 v[130:133], v[142:145], v[166:169], v[130:133]
	v_mfma_f32_16x16x32_bf16 v[108:111], v[126:129], v[174:177], v[108:111]
	v_mfma_f32_16x16x32_bf16 v[104:107], v[142:145], v[174:177], v[104:107]
	v_mfma_f32_16x16x32_bf16 v[92:95], v[126:129], v[182:185], v[92:95]
	v_mfma_f32_16x16x32_bf16 v[88:91], v[142:145], v[182:185], v[88:91]
	v_mfma_f32_16x16x32_bf16 v[76:79], v[126:129], v[212:215], v[76:79]
	v_mfma_f32_16x16x32_bf16 v[72:75], v[142:145], v[212:215], v[72:75]
	v_mfma_f32_16x16x32_bf16 v[118:121], v[146:149], v[162:165], v[118:121]
	v_mfma_f32_16x16x32_bf16 v[114:117], v[154:157], v[162:165], v[114:117]
	v_mfma_f32_16x16x32_bf16 v[100:103], v[146:149], v[170:173], v[100:103]
	v_mfma_f32_16x16x32_bf16 v[96:99], v[154:157], v[170:173], v[96:99]
	v_mfma_f32_16x16x32_bf16 v[84:87], v[146:149], v[178:181], v[84:87]
	v_mfma_f32_16x16x32_bf16 v[80:83], v[154:157], v[178:181], v[80:83]
	v_mfma_f32_16x16x32_bf16 v[68:71], v[146:149], v[208:211], v[68:71]
	v_mfma_f32_16x16x32_bf16 v[64:67], v[154:157], v[208:211], v[64:67]
	v_mfma_f32_16x16x32_bf16 v[118:121], v[150:153], v[166:169], v[118:121]
	v_mfma_f32_16x16x32_bf16 v[114:117], v[158:161], v[166:169], v[114:117]
	v_mfma_f32_16x16x32_bf16 v[100:103], v[150:153], v[174:177], v[100:103]
	v_mfma_f32_16x16x32_bf16 v[96:99], v[158:161], v[174:177], v[96:99]
	v_mfma_f32_16x16x32_bf16 v[84:87], v[150:153], v[182:185], v[84:87]
	v_mfma_f32_16x16x32_bf16 v[80:83], v[158:161], v[182:185], v[80:83]
	v_mfma_f32_16x16x32_bf16 v[68:71], v[150:153], v[212:215], v[68:71]
	v_mfma_f32_16x16x32_bf16 v[64:67], v[158:161], v[212:215], v[64:67]
	s_barrier
; #define PG8_STAGE(bufoff, gbase, voff) do { _Pragma("unroll") for (int _i = 0; _i < 2; ++_i) \
;         __builtin_amdgcn_global_load_lds((const unsigned*)((const char*)(gbase) + (voff)[_i]), (PG8_LAS unsigned*)(lds + (bufoff) + ldsw + _i * 8192), 16, 0, 0); } while (0)
; #define PG8_LDA(dst, b, h) do { _Pragma("unroll") for (int m = 0; m < 4; ++m) _Pragma("unroll") for (int k = 0; k < 2; ++k) dst[m][k] = *(const PG8_LAS bf16x8*)(lds + PG8_SA(b, h) + aoff + m * 2048 + k * 1024); } while (0)
; #define PG8_MMA(ai, bj, At, Bt) do { __builtin_amdgcn_s_setprio(1); _Pragma("unroll") for (int m = 0; m < 4; ++m) _Pragma("unroll") for (int n = 0; n < 2; ++n) _Pragma("unroll") for (int k = 0; k < 2; ++k) \
;         acc[ai][bj][m][n] = __builtin_amdgcn_mfma_f32_16x16x32_bf16(Bt[n][k], At[m][k], acc[ai][bj][m][n], 0, 0, 0); __builtin_amdgcn_s_setprio(0); } while (0)
; #define PG8_WAIT_V(n) asm volatile("s_waitcnt vmcnt(" #n ")" ::: "memory")
; #define PG8_WAIT_L(n) asm volatile("s_waitcnt lgkmcnt(" #n ")" ::: "memory")
; #define PG8_BAR __builtin_amdgcn_s_barrier()
; #define PG8_SCHED __builtin_amdgcn_sched_barrier(0)
; template <class Epi, class Sched, bool ALIGN_EPI = false, bool SP2 = false>
; __device__ __forceinline__ void gemm_phase(PG8_LAS unsigned char* lds, const Gemm g, const Sched& S, const Epi& E) {
;     ...
;             PG8_LDA(At, 1, 1); PG8_STAGE(PG8_SB(1, 0), b3, voffB); PG8_STAGE(PG8_SB(1, 1), b3 + hstepB, voffB); PG8_STAGE(PG8_SA(1, 0), a3, voffA);
;             PG8_WAIT_V(8); PG8_WAIT_L(0); PG8_BAR; PG8_MMA(1, 0, At, B0); PG8_MMA(1, 1, At, B1); PG8_BAR; PG8_SCHED;
	s_add_i32 s24, s51, s36
	v_lshl_add_u64 v[196:197], v[196:197], 0, s[2:3]
	s_mov_b32 m0, s24
	ds_read_b128 v[162:165], v231 offset:49152
	ds_read_b128 v[166:169], v231 offset:50176
	ds_read_b128 v[170:173], v231 offset:51200
	ds_read_b128 v[174:177], v231 offset:52224
	ds_read_b128 v[178:181], v231 offset:53248
	ds_read_b128 v[182:185], v231 offset:54272
	ds_read_b128 v[208:211], v231 offset:55296
	ds_read_b128 v[212:215], v231 offset:56320
	global_load_lds_dwordx4 v[196:197], off
	s_add_i32 m0, s24, 0x2000
	s_add_u32 s24, s26, 0x20080
	v_lshl_add_u64 v[196:197], v[198:199], 0, s[2:3]
	s_addc_u32 s25, s27, 0
	s_add_i32 s26, s52, s36
	global_load_lds_dwordx4 v[196:197], off
	v_lshl_add_u64 v[196:197], s[24:25], 0, v[112:113]
	s_mov_b32 m0, s26
	s_nop 0
	global_load_lds_dwordx4 v[196:197], off
	v_lshl_add_u64 v[196:197], s[24:25], 0, v[186:187]
	s_add_i32 m0, s26, 0x2000
	s_nop 0
	global_load_lds_dwordx4 v[196:197], off
	v_lshl_add_u64 v[196:197], v[202:203], 0, s[2:3]
	s_mov_b32 m0, s41
	s_nop 0
	global_load_lds_dwordx4 v[196:197], off
	v_lshl_add_u64 v[196:197], v[204:205], 0, s[2:3]
	s_mov_b32 m0, s42
	s_nop 0
	global_load_lds_dwordx4 v[196:197], off
	s_waitcnt vmcnt(8)
	s_waitcnt lgkmcnt(0)
	s_barrier
	s_waitcnt lgkmcnt(0)
	v_mfma_f32_16x16x32_bf16 v[60:63], v[122:125], v[162:165], v[60:63]
	v_mfma_f32_16x16x32_bf16 v[56:59], v[138:141], v[162:165], v[56:59]
	v_mfma_f32_16x16x32_bf16 v[44:47], v[122:125], v[170:173], v[44:47]
	v_mfma_f32_16x16x32_bf16 v[40:43], v[138:141], v[170:173], v[40:43]
	v_mfma_f32_16x16x32_bf16 v[28:31], v[122:125], v[178:181], v[28:31]
	v_mfma_f32_16x16x32_bf16 v[24:27], v[138:141], v[178:181], v[24:27]
	v_mfma_f32_16x16x32_bf16 v[12:15], v[122:125], v[208:211], v[12:15]
	v_mfma_f32_16x16x32_bf16 v[8:11], v[138:141], v[208:211], v[8:11]
	v_mfma_f32_16x16x32_bf16 v[60:63], v[126:129], v[166:169], v[60:63]
	v_mfma_f32_16x16x32_bf16 v[56:59], v[142:145], v[166:169], v[56:59]
	v_mfma_f32_16x16x32_bf16 v[44:47], v[126:129], v[174:177], v[44:47]
	v_mfma_f32_16x16x32_bf16 v[40:43], v[142:145], v[174:177], v[40:43]
	v_mfma_f32_16x16x32_bf16 v[28:31], v[126:129], v[182:185], v[28:31]
	v_mfma_f32_16x16x32_bf16 v[24:27], v[142:145], v[182:185], v[24:27]
	v_mfma_f32_16x16x32_bf16 v[12:15], v[126:129], v[212:215], v[12:15]
	v_mfma_f32_16x16x32_bf16 v[8:11], v[142:145], v[212:215], v[8:11]
	v_mfma_f32_16x16x32_bf16 v[52:55], v[146:149], v[162:165], v[52:55]
	v_mfma_f32_16x16x32_bf16 v[48:51], v[154:157], v[162:165], v[48:51]
	v_mfma_f32_16x16x32_bf16 v[36:39], v[146:149], v[170:173], v[36:39]
	v_mfma_f32_16x16x32_bf16 v[32:35], v[154:157], v[170:173], v[32:35]
	v_mfma_f32_16x16x32_bf16 v[20:23], v[146:149], v[178:181], v[20:23]
	v_mfma_f32_16x16x32_bf16 v[16:19], v[154:157], v[178:181], v[16:19]
	v_mfma_f32_16x16x32_bf16 v[4:7], v[146:149], v[208:211], v[4:7]
	v_mfma_f32_16x16x32_bf16 v[0:3], v[154:157], v[208:211], v[0:3]
	v_mfma_f32_16x16x32_bf16 v[52:55], v[150:153], v[166:169], v[52:55]
	v_mfma_f32_16x16x32_bf16 v[48:51], v[158:161], v[166:169], v[48:51]
	v_mfma_f32_16x16x32_bf16 v[36:39], v[150:153], v[174:177], v[36:39]
	v_mfma_f32_16x16x32_bf16 v[32:35], v[158:161], v[174:177], v[32:35]
	v_mfma_f32_16x16x32_bf16 v[20:23], v[150:153], v[182:185], v[20:23]
	v_mfma_f32_16x16x32_bf16 v[16:19], v[158:161], v[182:185], v[16:19]
	v_mfma_f32_16x16x32_bf16 v[4:7], v[150:153], v[212:215], v[4:7]
	v_mfma_f32_16x16x32_bf16 v[0:3], v[158:161], v[212:215], v[0:3]
	s_barrier
	s_add_i32 s50, s50, 2
	s_add_u32 s48, s48, 0x100
	s_addc_u32 s49, s49, 0
	s_cmp_gt_u32 s50, 5
	s_mov_b64 s[24:25], s[6:7]
	s_cbranch_scc0 .LBB0_356
	s_and_b64 vcc, exec, s[16:17]
	s_cbranch_vccz .LBB0_359
	s_barrier

; #define PG8_STAGE(bufoff, gbase, voff) do { _Pragma("unroll") for (int _i = 0; _i < 2; ++_i) \
;         __builtin_amdgcn_global_load_lds((const unsigned*)((const char*)(gbase) + (voff)[_i]), (PG8_LAS unsigned*)(lds + (bufoff) + ldsw + _i * 8192), 16, 0, 0); } while (0)
; #define PG8_LDA(dst, b, h) do { _Pragma("unroll") for (int m = 0; m < 4; ++m) _Pragma("unroll") for (int k = 0; k < 2; ++k) dst[m][k] = *(const PG8_LAS bf16x8*)(lds + PG8_SA(b, h) + aoff + m * 2048 + k * 1024); } while (0)
; #define PG8_LDB(dst, b, h) do { _Pragma("unroll") for (int n = 0; n < 2; ++n) _Pragma("unroll") for (int k = 0; k < 2; ++k) dst[n][k] = *(const PG8_LAS bf16x8*)(lds + PG8_SB(b, h) + boff + n * 2048 + k * 1024); } while (0)
; #define PG8_MMA(ai, bj, At, Bt) do { __builtin_amdgcn_s_setprio(1); _Pragma("unroll") for (int m = 0; m < 4; ++m) _Pragma("unroll") for (int n = 0; n < 2; ++n) _Pragma("unroll") for (int k = 0; k < 2; ++k) \
;         acc[ai][bj][m][n] = __builtin_amdgcn_mfma_f32_16x16x32_bf16(Bt[n][k], At[m][k], acc[ai][bj][m][n], 0, 0, 0); __builtin_amdgcn_s_setprio(0); } while (0)
; #define PG8_WAIT_V(n) asm volatile("s_waitcnt vmcnt(" #n ")" ::: "memory")
; #define PG8_WAIT_L(n) asm volatile("s_waitcnt lgkmcnt(" #n ")" ::: "memory")
; #define PG8_BAR __builtin_amdgcn_s_barrier()
; template <class Epi, class Sched, bool ALIGN_EPI = false, bool SP2 = false>
; __device__ __forceinline__ void gemm_phase(PG8_LAS unsigned char* lds, const Gemm g, const Sched& S, const Epi& E) {
;     ...
;             const char* a1 = cA + (size_t)(t + 1) * kstep;
;             const char* a2 = last ? nA : cA + (size_t)(t + 2) * kstep; const char* b2 = last ? nB : cB + (size_t)(t + 2) * kstep;
;             const char* a3 = a2 + kstep; const char* b3 = b2 + kstep;
;             if (last && has_next) S.a_ready(nxt);
;             if constexpr (SP2) {
;             PG8_LDB(B0, 0, 0); PG8_LDB(B1, 0, 1); PG8_SCHED; PG8_LDA(At, 0, 0); PG8_STAGE(PG8_SA(1, 1), a1 + hstepA, voffA);
;             PG8_WAIT_V(8); PG8_WAIT_L(0); PG8_BAR; PG8_MMA(0, 0, At, B0); PG8_MMA(0, 1, At, B1); PG8_BAR; PG8_SCHED;
;             PG8_LDA(At, 0, 1); PG8_STAGE(PG8_SB(0, 0), b2, voffB); PG8_STAGE(PG8_SB(0, 1), b2 + hstepB, voffB); PG8_STAGE(PG8_SA(0, 0), a2, voffA);
;             PG8_WAIT_V(8); PG8_WAIT_L(0); PG8_BAR; PG8_MMA(1, 0, At, B0); PG8_MMA(1, 1, At, B1); PG8_BAR; PG8_SCHED;
.LBB0_410:
	s_add_u32 s8, s24, 0x100
	s_addc_u32 s9, s25, 0
	s_add_i32 s49, 0, 0x10000
	s_cmp_eq_u32 s48, 4
	s_cselect_b32 s29, s21, s9
	s_cselect_b32 s28, s20, s8
	v_add_u32_e32 v145, s49, v143
	s_cselect_b32 s27, s19, s47
	s_cselect_b32 s26, s45, s46
	s_add_i32 s50, 0, 0x14000
	ds_read_b128 v[146:149], v145
	ds_read_b128 v[150:153], v145 offset:1024
	ds_read_b128 v[154:157], v145 offset:2048
	ds_read_b128 v[158:161], v145 offset:3072
	v_add_u32_e32 v145, s50, v143
	ds_read_b128 v[162:165], v145
	ds_read_b128 v[166:169], v145 offset:1024
	ds_read_b128 v[170:173], v145 offset:2048
	ds_read_b128 v[174:177], v145 offset:3072
	v_lshl_add_u64 v[196:197], s[24:25], 0, v[140:141]
	s_add_i32 m0, s35, 0xc000
	ds_read_b128 v[178:181], v144
	ds_read_b128 v[182:185], v144 offset:1024
	ds_read_b128 v[186:189], v144 offset:2048
	ds_read_b128 v[190:193], v144 offset:3072
	ds_read_b128 v[206:209], v144 offset:4096
	ds_read_b128 v[210:213], v144 offset:5120
	ds_read_b128 v[214:217], v144 offset:6144
	ds_read_b128 v[218:221], v144 offset:7168
	global_load_lds_dwordx4 v[196:197], off
	v_lshl_add_u64 v[196:197], s[24:25], 0, v[138:139]
	s_add_i32 m0, s35, 0xe000
	s_nop 0
	global_load_lds_dwordx4 v[196:197], off
	s_waitcnt vmcnt(8)
	s_waitcnt lgkmcnt(0)
	s_barrier
	s_waitcnt lgkmcnt(0)
	v_mfma_f32_16x16x32_bf16 v[126:129], v[146:149], v[178:181], v[126:129]
	v_mfma_f32_16x16x32_bf16 v[122:125], v[154:157], v[178:181], v[122:125]
	v_mfma_f32_16x16x32_bf16 v[114:117], v[146:149], v[186:189], v[114:117]
	v_mfma_f32_16x16x32_bf16 v[104:107], v[154:157], v[186:189], v[104:107]
	v_mfma_f32_16x16x32_bf16 v[96:99], v[146:149], v[206:209], v[96:99]
	v_mfma_f32_16x16x32_bf16 v[88:91], v[154:157], v[206:209], v[88:91]
	v_mfma_f32_16x16x32_bf16 v[80:83], v[146:149], v[214:217], v[80:83]
	v_mfma_f32_16x16x32_bf16 v[72:75], v[154:157], v[214:217], v[72:75]
	v_mfma_f32_16x16x32_bf16 v[126:129], v[150:153], v[182:185], v[126:129]
	v_mfma_f32_16x16x32_bf16 v[122:125], v[158:161], v[182:185], v[122:125]
	v_mfma_f32_16x16x32_bf16 v[114:117], v[150:153], v[190:193], v[114:117]
	v_mfma_f32_16x16x32_bf16 v[104:107], v[158:161], v[190:193], v[104:107]
	v_mfma_f32_16x16x32_bf16 v[96:99], v[150:153], v[210:213], v[96:99]
	v_mfma_f32_16x16x32_bf16 v[88:91], v[158:161], v[210:213], v[88:91]
	v_mfma_f32_16x16x32_bf16 v[80:83], v[150:153], v[218:221], v[80:83]
	v_mfma_f32_16x16x32_bf16 v[72:75], v[158:161], v[218:221], v[72:75]
	v_mfma_f32_16x16x32_bf16 v[118:121], v[162:165], v[178:181], v[118:121]
	v_mfma_f32_16x16x32_bf16 v[108:111], v[170:173], v[178:181], v[108:111]
	v_mfma_f32_16x16x32_bf16 v[100:103], v[162:165], v[186:189], v[100:103]
	v_mfma_f32_16x16x32_bf16 v[92:95], v[170:173], v[186:189], v[92:95]
	v_mfma_f32_16x16x32_bf16 v[84:87], v[162:165], v[206:209], v[84:87]
	v_mfma_f32_16x16x32_bf16 v[76:79], v[170:173], v[206:209], v[76:79]
	v_mfma_f32_16x16x32_bf16 v[68:71], v[162:165], v[214:217], v[68:71]
	v_mfma_f32_16x16x32_bf16 v[64:67], v[170:173], v[214:217], v[64:67]
	v_mfma_f32_16x16x32_bf16 v[118:121], v[166:169], v[182:185], v[118:121]
	v_mfma_f32_16x16x32_bf16 v[108:111], v[174:177], v[182:185], v[108:111]
	v_mfma_f32_16x16x32_bf16 v[100:103], v[166:169], v[190:193], v[100:103]
	v_mfma_f32_16x16x32_bf16 v[92:95], v[174:177], v[190:193], v[92:95]
	v_mfma_f32_16x16x32_bf16 v[84:87], v[166:169], v[210:213], v[84:87]
	v_mfma_f32_16x16x32_bf16 v[76:79], v[174:177], v[210:213], v[76:79]
	v_mfma_f32_16x16x32_bf16 v[68:71], v[166:169], v[218:221], v[68:71]
	v_mfma_f32_16x16x32_bf16 v[64:67], v[174:177], v[218:221], v[64:67]
	s_barrier
	s_add_i32 s24, s49, s34
	v_lshl_add_u64 v[196:197], s[26:27], 0, v[134:135]
	s_mov_b32 m0, s24
	ds_read_b128 v[178:181], v144 offset:16384
	ds_read_b128 v[182:185], v144 offset:17408
	ds_read_b128 v[186:189], v144 offset:18432
	ds_read_b128 v[190:193], v144 offset:19456
	ds_read_b128 v[206:209], v144 offset:20480
	ds_read_b128 v[210:213], v144 offset:21504
	ds_read_b128 v[214:217], v144 offset:22528
	ds_read_b128 v[218:221], v144 offset:23552
	global_load_lds_dwordx4 v[196:197], off
	s_add_i32 m0, s24, 0x2000
	s_add_u32 s24, s26, 0x20000
	v_lshl_add_u64 v[198:199], s[26:27], 0, v[130:131]
	s_addc_u32 s25, s27, 0
	s_add_i32 s49, s50, s34
	global_load_lds_dwordx4 v[198:199], off
	v_lshl_add_u64 v[202:203], s[24:25], 0, v[134:135]
	s_mov_b32 m0, s49
	v_lshl_add_u64 v[204:205], s[28:29], 0, v[132:133]
	global_load_lds_dwordx4 v[202:203], off
	v_lshl_add_u64 v[202:203], s[24:25], 0, v[130:131]
	s_add_i32 m0, s49, 0x2000
	s_nop 0
	global_load_lds_dwordx4 v[202:203], off
	v_lshl_add_u64 v[202:203], s[28:29], 0, v[136:137]
	s_mov_b32 m0, s35
	s_nop 0
	global_load_lds_dwordx4 v[202:203], off
	s_mov_b32 m0, s36
	s_nop 0
	global_load_lds_dwordx4 v[204:205], off
	s_waitcnt vmcnt(8)
	s_waitcnt lgkmcnt(0)
	s_barrier
; #define PG8_STAGE(bufoff, gbase, voff) do { _Pragma("unroll") for (int _i = 0; _i < 2; ++_i) \
;         __builtin_amdgcn_global_load_lds((const unsigned*)((const char*)(gbase) + (voff)[_i]), (PG8_LAS unsigned*)(lds + (bufoff) + ldsw + _i * 8192), 16, 0, 0); } while (0)
; #define PG8_LDA(dst, b, h) do { _Pragma("unroll") for (int m = 0; m < 4; ++m) _Pragma("unroll") for (int k = 0; k < 2; ++k) dst[m][k] = *(const PG8_LAS bf16x8*)(lds + PG8_SA(b, h) + aoff + m * 2048 + k * 1024); } while (0)
; #define PG8_LDB(dst, b, h) do { _Pragma("unroll") for (int n = 0; n < 2; ++n) _Pragma("unroll") for (int k = 0; k < 2; ++k) dst[n][k] = *(const PG8_LAS bf16x8*)(lds + PG8_SB(b, h) + boff + n * 2048 + k * 1024); } while (0)
; #define PG8_MMA(ai, bj, At, Bt) do { __builtin_amdgcn_s_setprio(1); _Pragma("unroll") for (int m = 0; m < 4; ++m) _Pragma("unroll") for (int n = 0; n < 2; ++n) _Pragma("unroll") for (int k = 0; k < 2; ++k) \
;         acc[ai][bj][m][n] = __builtin_amdgcn_mfma_f32_16x16x32_bf16(Bt[n][k], At[m][k], acc[ai][bj][m][n], 0, 0, 0); __builtin_amdgcn_s_setprio(0); } while (0)
; #define PG8_WAIT_V(n) asm volatile("s_waitcnt vmcnt(" #n ")" ::: "memory")
; #define PG8_WAIT_L(n) asm volatile("s_waitcnt lgkmcnt(" #n ")" ::: "memory")
; #define PG8_BAR __builtin_amdgcn_s_barrier()
; #define PG8_SCHED __builtin_amdgcn_sched_barrier(0)
; template <class Epi, class Sched, bool ALIGN_EPI = false, bool SP2 = false>
; __device__ __forceinline__ void gemm_phase(PG8_LAS unsigned char* lds, const Gemm g, const Sched& S, const Epi& E) {
;     ...
;             PG8_WAIT_V(8); PG8_WAIT_L(0); PG8_BAR; PG8_MMA(1, 0, At, B0); PG8_MMA(1, 1, At, B1); PG8_BAR; PG8_SCHED;
;             PG8_LDB(B0, 1, 0); PG8_LDB(B1, 1, 1); PG8_SCHED; PG8_LDA(At, 1, 0); PG8_STAGE(PG8_SA(0, 1), a2 + hstepA, voffA);
;             PG8_WAIT_V(8); PG8_WAIT_L(0); PG8_BAR; PG8_MMA(0, 0, At, B0); PG8_MMA(0, 1, At, B1); PG8_BAR; PG8_SCHED;
;             PG8_LDA(At, 1, 1); PG8_STAGE(PG8_SB(1, 0), b3, voffB); PG8_STAGE(PG8_SB(1, 1), b3 + hstepB, voffB); PG8_STAGE(PG8_SA(1, 0), a3, voffA);
	s_waitcnt lgkmcnt(0)
	v_mfma_f32_16x16x32_bf16 v[60:63], v[146:149], v[178:181], v[60:63]
	v_mfma_f32_16x16x32_bf16 v[56:59], v[154:157], v[178:181], v[56:59]
	v_mfma_f32_16x16x32_bf16 v[48:51], v[146:149], v[186:189], v[48:51]
	v_mfma_f32_16x16x32_bf16 v[40:43], v[154:157], v[186:189], v[40:43]
	v_mfma_f32_16x16x32_bf16 v[32:35], v[146:149], v[206:209], v[32:35]
	v_mfma_f32_16x16x32_bf16 v[24:27], v[154:157], v[206:209], v[24:27]
	v_mfma_f32_16x16x32_bf16 v[16:19], v[146:149], v[214:217], v[16:19]
	v_mfma_f32_16x16x32_bf16 v[8:11], v[154:157], v[214:217], v[8:11]
	v_mfma_f32_16x16x32_bf16 v[60:63], v[150:153], v[182:185], v[60:63]
	v_mfma_f32_16x16x32_bf16 v[56:59], v[158:161], v[182:185], v[56:59]
	v_mfma_f32_16x16x32_bf16 v[48:51], v[150:153], v[190:193], v[48:51]
	v_mfma_f32_16x16x32_bf16 v[40:43], v[158:161], v[190:193], v[40:43]
	v_mfma_f32_16x16x32_bf16 v[32:35], v[150:153], v[210:213], v[32:35]
	v_mfma_f32_16x16x32_bf16 v[24:27], v[158:161], v[210:213], v[24:27]
	v_mfma_f32_16x16x32_bf16 v[16:19], v[150:153], v[218:221], v[16:19]
	v_mfma_f32_16x16x32_bf16 v[8:11], v[158:161], v[218:221], v[8:11]
	v_mfma_f32_16x16x32_bf16 v[52:55], v[162:165], v[178:181], v[52:55]
	v_mfma_f32_16x16x32_bf16 v[44:47], v[170:173], v[178:181], v[44:47]
	v_mfma_f32_16x16x32_bf16 v[36:39], v[162:165], v[186:189], v[36:39]
	v_mfma_f32_16x16x32_bf16 v[28:31], v[170:173], v[186:189], v[28:31]
	v_mfma_f32_16x16x32_bf16 v[20:23], v[162:165], v[206:209], v[20:23]
	v_mfma_f32_16x16x32_bf16 v[12:15], v[170:173], v[206:209], v[12:15]
	v_mfma_f32_16x16x32_bf16 v[4:7], v[162:165], v[214:217], v[4:7]
	v_mfma_f32_16x16x32_bf16 v[0:3], v[170:173], v[214:217], v[0:3]
	v_mfma_f32_16x16x32_bf16 v[52:55], v[166:169], v[182:185], v[52:55]
	v_mfma_f32_16x16x32_bf16 v[44:47], v[174:177], v[182:185], v[44:47]
	v_mfma_f32_16x16x32_bf16 v[36:39], v[166:169], v[190:193], v[36:39]
	v_mfma_f32_16x16x32_bf16 v[28:31], v[174:177], v[190:193], v[28:31]
	v_mfma_f32_16x16x32_bf16 v[20:23], v[166:169], v[210:213], v[20:23]
	v_mfma_f32_16x16x32_bf16 v[12:15], v[174:177], v[210:213], v[12:15]
	v_mfma_f32_16x16x32_bf16 v[4:7], v[166:169], v[218:221], v[4:7]
	v_mfma_f32_16x16x32_bf16 v[0:3], v[174:177], v[218:221], v[0:3]
	s_barrier
	s_add_i32 s49, 0, 0x18000
	v_add_u32_e32 v145, s49, v143
	s_add_i32 s50, 0, 0x1c000
	ds_read_b128 v[146:149], v145
	ds_read_b128 v[150:153], v145 offset:1024
	ds_read_b128 v[154:157], v145 offset:2048
	ds_read_b128 v[158:161], v145 offset:3072
	v_add_u32_e32 v145, s50, v143
	ds_read_b128 v[162:165], v145
	ds_read_b128 v[166:169], v145 offset:1024
	ds_read_b128 v[170:173], v145 offset:2048
	ds_read_b128 v[174:177], v145 offset:3072
	s_add_u32 s24, s28, 0x150000
	s_addc_u32 s25, s29, 0
	s_mov_b32 m0, s37
	v_lshl_add_u64 v[222:223], s[24:25], 0, v[136:137]
	ds_read_b128 v[178:181], v144 offset:32768
	ds_read_b128 v[182:185], v144 offset:33792
	ds_read_b128 v[186:189], v144 offset:34816
	ds_read_b128 v[190:193], v144 offset:35840
	ds_read_b128 v[206:209], v144 offset:36864
	ds_read_b128 v[210:213], v144 offset:37888
	ds_read_b128 v[214:217], v144 offset:38912
	ds_read_b128 v[218:221], v144 offset:39936
	global_load_lds_dwordx4 v[222:223], off
	v_lshl_add_u64 v[222:223], s[24:25], 0, v[132:133]
	s_mov_b32 m0, s38
	s_nop 0
	global_load_lds_dwordx4 v[222:223], off
	s_waitcnt vmcnt(8)
	s_waitcnt lgkmcnt(0)
	s_barrier
	s_waitcnt lgkmcnt(0)
	v_mfma_f32_16x16x32_bf16 v[126:129], v[146:149], v[178:181], v[126:129]
	v_mfma_f32_16x16x32_bf16 v[122:125], v[154:157], v[178:181], v[122:125]
	v_mfma_f32_16x16x32_bf16 v[114:117], v[146:149], v[186:189], v[114:117]
	v_mfma_f32_16x16x32_bf16 v[104:107], v[154:157], v[186:189], v[104:107]
	v_mfma_f32_16x16x32_bf16 v[96:99], v[146:149], v[206:209], v[96:99]
	v_mfma_f32_16x16x32_bf16 v[88:91], v[154:157], v[206:209], v[88:91]
	v_mfma_f32_16x16x32_bf16 v[80:83], v[146:149], v[214:217], v[80:83]
	v_mfma_f32_16x16x32_bf16 v[72:75], v[154:157], v[214:217], v[72:75]
	v_mfma_f32_16x16x32_bf16 v[126:129], v[150:153], v[182:185], v[126:129]
	v_mfma_f32_16x16x32_bf16 v[122:125], v[158:161], v[182:185], v[122:125]
	v_mfma_f32_16x16x32_bf16 v[114:117], v[150:153], v[190:193], v[114:117]
	v_mfma_f32_16x16x32_bf16 v[104:107], v[158:161], v[190:193], v[104:107]
	v_mfma_f32_16x16x32_bf16 v[96:99], v[150:153], v[210:213], v[96:99]
	v_mfma_f32_16x16x32_bf16 v[88:91], v[158:161], v[210:213], v[88:91]
	v_mfma_f32_16x16x32_bf16 v[80:83], v[150:153], v[218:221], v[80:83]
	v_mfma_f32_16x16x32_bf16 v[72:75], v[158:161], v[218:221], v[72:75]
	v_mfma_f32_16x16x32_bf16 v[118:121], v[162:165], v[178:181], v[118:121]
	v_mfma_f32_16x16x32_bf16 v[108:111], v[170:173], v[178:181], v[108:111]
	v_mfma_f32_16x16x32_bf16 v[100:103], v[162:165], v[186:189], v[100:103]
	v_mfma_f32_16x16x32_bf16 v[92:95], v[170:173], v[186:189], v[92:95]
	v_mfma_f32_16x16x32_bf16 v[84:87], v[162:165], v[206:209], v[84:87]
	v_mfma_f32_16x16x32_bf16 v[76:79], v[170:173], v[206:209], v[76:79]
	v_mfma_f32_16x16x32_bf16 v[68:71], v[162:165], v[214:217], v[68:71]
	v_mfma_f32_16x16x32_bf16 v[64:67], v[170:173], v[214:217], v[64:67]
	v_mfma_f32_16x16x32_bf16 v[118:121], v[166:169], v[182:185], v[118:121]
	v_mfma_f32_16x16x32_bf16 v[108:111], v[174:177], v[182:185], v[108:111]
	v_mfma_f32_16x16x32_bf16 v[100:103], v[166:169], v[190:193], v[100:103]
	v_mfma_f32_16x16x32_bf16 v[92:95], v[174:177], v[190:193], v[92:95]
	v_mfma_f32_16x16x32_bf16 v[84:87], v[166:169], v[210:213], v[84:87]
	v_mfma_f32_16x16x32_bf16 v[76:79], v[174:177], v[210:213], v[76:79]
	v_mfma_f32_16x16x32_bf16 v[68:71], v[166:169], v[218:221], v[68:71]
	v_mfma_f32_16x16x32_bf16 v[64:67], v[174:177], v[218:221], v[64:67]
	s_barrier
; #define PG8_STAGE(bufoff, gbase, voff) do { _Pragma("unroll") for (int _i = 0; _i < 2; ++_i) \
;         __builtin_amdgcn_global_load_lds((const unsigned*)((const char*)(gbase) + (voff)[_i]), (PG8_LAS unsigned*)(lds + (bufoff) + ldsw + _i * 8192), 16, 0, 0); } while (0)
; #define PG8_LDA(dst, b, h) do { _Pragma("unroll") for (int m = 0; m < 4; ++m) _Pragma("unroll") for (int k = 0; k < 2; ++k) dst[m][k] = *(const PG8_LAS bf16x8*)(lds + PG8_SA(b, h) + aoff + m * 2048 + k * 1024); } while (0)
; #define PG8_MMA(ai, bj, At, Bt) do { __builtin_amdgcn_s_setprio(1); _Pragma("unroll") for (int m = 0; m < 4; ++m) _Pragma("unroll") for (int n = 0; n < 2; ++n) _Pragma("unroll") for (int k = 0; k < 2; ++k) \
;         acc[ai][bj][m][n] = __builtin_amdgcn_mfma_f32_16x16x32_bf16(Bt[n][k], At[m][k], acc[ai][bj][m][n], 0, 0, 0); __builtin_amdgcn_s_setprio(0); } while (0)
; #define PG8_WAIT_V(n) asm volatile("s_waitcnt vmcnt(" #n ")" ::: "memory")
; #define PG8_WAIT_L(n) asm volatile("s_waitcnt lgkmcnt(" #n ")" ::: "memory")
; #define PG8_BAR __builtin_amdgcn_s_barrier()
; #define PG8_SCHED __builtin_amdgcn_sched_barrier(0)
; template <class Epi, class Sched, bool ALIGN_EPI = false, bool SP2 = false>
; __device__ __forceinline__ void gemm_phase(PG8_LAS unsigned char* lds, const Gemm g, const Sched& S, const Epi& E) {
;     ...
;             PG8_LDA(At, 1, 1); PG8_STAGE(PG8_SB(1, 0), b3, voffB); PG8_STAGE(PG8_SB(1, 1), b3 + hstepB, voffB); PG8_STAGE(PG8_SA(1, 0), a3, voffA);
;             PG8_WAIT_V(8); PG8_WAIT_L(0); PG8_BAR; PG8_MMA(1, 0, At, B0); PG8_MMA(1, 1, At, B1); PG8_BAR; PG8_SCHED;
	s_add_i32 s24, s49, s34
	v_lshl_add_u64 v[196:197], v[196:197], 0, s[2:3]
	s_mov_b32 m0, s24
	ds_read_b128 v[178:181], v144 offset:49152
	ds_read_b128 v[182:185], v144 offset:50176
	ds_read_b128 v[186:189], v144 offset:51200
	ds_read_b128 v[190:193], v144 offset:52224
	ds_read_b128 v[206:209], v144 offset:53248
	ds_read_b128 v[210:213], v144 offset:54272
	ds_read_b128 v[214:217], v144 offset:55296
	ds_read_b128 v[218:221], v144 offset:56320
	global_load_lds_dwordx4 v[196:197], off
	s_add_i32 m0, s24, 0x2000
	s_add_u32 s24, s26, 0x20080
	v_lshl_add_u64 v[196:197], v[198:199], 0, s[2:3]
	s_addc_u32 s25, s27, 0
	s_add_i32 s26, s50, s34
	global_load_lds_dwordx4 v[196:197], off
	v_lshl_add_u64 v[196:197], s[24:25], 0, v[134:135]
	s_mov_b32 m0, s26
	s_nop 0
	global_load_lds_dwordx4 v[196:197], off
	v_lshl_add_u64 v[196:197], s[24:25], 0, v[130:131]
	s_add_i32 m0, s26, 0x2000
	s_nop 0
	global_load_lds_dwordx4 v[196:197], off
	v_lshl_add_u64 v[196:197], v[202:203], 0, s[2:3]
	s_mov_b32 m0, s39
	s_nop 0
	global_load_lds_dwordx4 v[196:197], off
	v_lshl_add_u64 v[196:197], v[204:205], 0, s[2:3]
	s_mov_b32 m0, s40
	s_nop 0
	global_load_lds_dwordx4 v[196:197], off
	s_waitcnt vmcnt(8)
	s_waitcnt lgkmcnt(0)
	s_barrier
	s_waitcnt lgkmcnt(0)
	v_mfma_f32_16x16x32_bf16 v[60:63], v[146:149], v[178:181], v[60:63]
	v_mfma_f32_16x16x32_bf16 v[56:59], v[154:157], v[178:181], v[56:59]
	v_mfma_f32_16x16x32_bf16 v[48:51], v[146:149], v[186:189], v[48:51]
	v_mfma_f32_16x16x32_bf16 v[40:43], v[154:157], v[186:189], v[40:43]
	v_mfma_f32_16x16x32_bf16 v[32:35], v[146:149], v[206:209], v[32:35]
	v_mfma_f32_16x16x32_bf16 v[24:27], v[154:157], v[206:209], v[24:27]
	v_mfma_f32_16x16x32_bf16 v[16:19], v[146:149], v[214:217], v[16:19]
	v_mfma_f32_16x16x32_bf16 v[8:11], v[154:157], v[214:217], v[8:11]
	v_mfma_f32_16x16x32_bf16 v[60:63], v[150:153], v[182:185], v[60:63]
	v_mfma_f32_16x16x32_bf16 v[56:59], v[158:161], v[182:185], v[56:59]
	v_mfma_f32_16x16x32_bf16 v[48:51], v[150:153], v[190:193], v[48:51]
	v_mfma_f32_16x16x32_bf16 v[40:43], v[158:161], v[190:193], v[40:43]
	v_mfma_f32_16x16x32_bf16 v[32:35], v[150:153], v[210:213], v[32:35]
	v_mfma_f32_16x16x32_bf16 v[24:27], v[158:161], v[210:213], v[24:27]
	v_mfma_f32_16x16x32_bf16 v[16:19], v[150:153], v[218:221], v[16:19]
	v_mfma_f32_16x16x32_bf16 v[8:11], v[158:161], v[218:221], v[8:11]
	v_mfma_f32_16x16x32_bf16 v[52:55], v[162:165], v[178:181], v[52:55]
	v_mfma_f32_16x16x32_bf16 v[44:47], v[170:173], v[178:181], v[44:47]
	v_mfma_f32_16x16x32_bf16 v[36:39], v[162:165], v[186:189], v[36:39]
	v_mfma_f32_16x16x32_bf16 v[28:31], v[170:173], v[186:189], v[28:31]
	v_mfma_f32_16x16x32_bf16 v[20:23], v[162:165], v[206:209], v[20:23]
	v_mfma_f32_16x16x32_bf16 v[12:15], v[170:173], v[206:209], v[12:15]
	v_mfma_f32_16x16x32_bf16 v[4:7], v[162:165], v[214:217], v[4:7]
	v_mfma_f32_16x16x32_bf16 v[0:3], v[170:173], v[214:217], v[0:3]
	v_mfma_f32_16x16x32_bf16 v[52:55], v[166:169], v[182:185], v[52:55]
	v_mfma_f32_16x16x32_bf16 v[44:47], v[174:177], v[182:185], v[44:47]
	v_mfma_f32_16x16x32_bf16 v[36:39], v[166:169], v[190:193], v[36:39]
	v_mfma_f32_16x16x32_bf16 v[28:31], v[174:177], v[190:193], v[28:31]
	v_mfma_f32_16x16x32_bf16 v[20:23], v[166:169], v[210:213], v[20:23]
	v_mfma_f32_16x16x32_bf16 v[12:15], v[174:177], v[210:213], v[12:15]
	v_mfma_f32_16x16x32_bf16 v[4:7], v[166:169], v[218:221], v[4:7]
	v_mfma_f32_16x16x32_bf16 v[0:3], v[174:177], v[218:221], v[0:3]
	s_barrier
	s_add_i32 s48, s48, 2
	s_add_u32 s46, s46, 0x100
	s_addc_u32 s47, s47, 0
	s_cmp_gt_u32 s48, 5
	s_mov_b64 s[24:25], s[8:9]
	s_cbranch_scc0 .LBB0_410
	s_and_b64 vcc, exec, s[16:17]
	s_cbranch_vccz .LBB0_413
	s_barrier

; #define PG8_STAGE(bufoff, gbase, voff) do { _Pragma("unroll") for (int _i = 0; _i < 2; ++_i) \
;         __builtin_amdgcn_global_load_lds((const unsigned*)((const char*)(gbase) + (voff)[_i]), (PG8_LAS unsigned*)(lds + (bufoff) + ldsw + _i * 8192), 16, 0, 0); } while (0)
; #define PG8_LDA(dst, b, h) do { _Pragma("unroll") for (int m = 0; m < 4; ++m) _Pragma("unroll") for (int k = 0; k < 2; ++k) dst[m][k] = *(const PG8_LAS bf16x8*)(lds + PG8_SA(b, h) + aoff + m * 2048 + k * 1024); } while (0)
; #define PG8_LDB(dst, b, h) do { _Pragma("unroll") for (int n = 0; n < 2; ++n) _Pragma("unroll") for (int k = 0; k < 2; ++k) dst[n][k] = *(const PG8_LAS bf16x8*)(lds + PG8_SB(b, h) + boff + n * 2048 + k * 1024); } while (0)
; #define PG8_MMA(ai, bj, At, Bt) do { __builtin_amdgcn_s_setprio(1); _Pragma("unroll") for (int m = 0; m < 4; ++m) _Pragma("unroll") for (int n = 0; n < 2; ++n) _Pragma("unroll") for (int k = 0; k < 2; ++k) \
;         acc[ai][bj][m][n] = __builtin_amdgcn_mfma_f32_16x16x32_bf16(Bt[n][k], At[m][k], acc[ai][bj][m][n], 0, 0, 0); __builtin_amdgcn_s_setprio(0); } while (0)
; #define PG8_WAIT_V(n) asm volatile("s_waitcnt vmcnt(" #n ")" ::: "memory")
; #define PG8_WAIT_L(n) asm volatile("s_waitcnt lgkmcnt(" #n ")" ::: "memory")
; #define PG8_BAR __builtin_amdgcn_s_barrier()
; template <class Epi, class Sched, bool ALIGN_EPI = false, bool SP2 = false>
; __device__ __forceinline__ void gemm_phase(PG8_LAS unsigned char* lds, const Gemm g, const Sched& S, const Epi& E) {
;     ...
;             const char* a1 = cA + (size_t)(t + 1) * kstep;
;             const char* a2 = last ? nA : cA + (size_t)(t + 2) * kstep; const char* b2 = last ? nB : cB + (size_t)(t + 2) * kstep;
;             const char* a3 = a2 + kstep; const char* b3 = b2 + kstep;
;             if (last && has_next) S.a_ready(nxt);
;             if constexpr (SP2) {
;             PG8_LDB(B0, 0, 0); PG8_LDB(B1, 0, 1); PG8_SCHED; PG8_LDA(At, 0, 0); PG8_STAGE(PG8_SA(1, 1), a1 + hstepA, voffA);
;             PG8_WAIT_V(8); PG8_WAIT_L(0); PG8_BAR; PG8_MMA(0, 0, At, B0); PG8_MMA(0, 1, At, B1); PG8_BAR; PG8_SCHED;
;             PG8_LDA(At, 0, 1); PG8_STAGE(PG8_SB(0, 0), b2, voffB); PG8_STAGE(PG8_SB(0, 1), b2 + hstepB, voffB); PG8_STAGE(PG8_SA(0, 0), a2, voffA);
;             PG8_WAIT_V(8); PG8_WAIT_L(0); PG8_BAR; PG8_MMA(1, 0, At, B0); PG8_MMA(1, 1, At, B1); PG8_BAR; PG8_SCHED;
.LBB0_591:
	s_add_u32 s30, s10, 0xfff80080
	s_addc_u32 s31, s11, -1
	s_add_i32 s56, 0, 0x10000
	s_cmp_eq_u32 s55, 28
	s_cselect_b32 s35, s25, s31
	s_cselect_b32 s34, s51, s30
	s_cselect_b32 s31, s23, s54
	s_cselect_b32 s30, s52, s53
	s_add_i32 s58, 0, 0x14000
	v_add_u32_e32 v142, s56, v244
	v_add_u32_e32 v158, s58, v244
	ds_read_b128 v[130:133], v142
	ds_read_b128 v[134:137], v142 offset:1024
	ds_read_b128 v[138:141], v142 offset:2048
	ds_read_b128 v[142:145], v142 offset:3072
	ds_read_b128 v[146:149], v158
	ds_read_b128 v[150:153], v158 offset:1024
	ds_read_b128 v[154:157], v158 offset:2048
	ds_read_b128 v[158:161], v158 offset:3072
	v_lshl_add_u64 v[196:197], s[10:11], 0, v[210:211]
	s_add_i32 m0, s41, 0xc000
	ds_read_b128 v[162:165], v246
	ds_read_b128 v[166:169], v246 offset:1024
	ds_read_b128 v[170:173], v246 offset:2048
	ds_read_b128 v[174:177], v246 offset:3072
	ds_read_b128 v[178:181], v246 offset:4096
	ds_read_b128 v[182:185], v246 offset:5120
	ds_read_b128 v[186:189], v246 offset:6144
	ds_read_b128 v[190:193], v246 offset:7168
	global_load_lds_dwordx4 v[196:197], off
	v_lshl_add_u64 v[196:197], s[10:11], 0, v[208:209]
	s_add_i32 m0, s41, 0xe000
	s_nop 0
	global_load_lds_dwordx4 v[196:197], off
	s_waitcnt vmcnt(8)
	s_waitcnt lgkmcnt(0)
	s_barrier
	s_waitcnt lgkmcnt(0)
	v_mfma_f32_16x16x32_bf16 v[126:129], v[130:133], v[162:165], v[126:129]
	v_mfma_f32_16x16x32_bf16 v[122:125], v[138:141], v[162:165], v[122:125]
	v_mfma_f32_16x16x32_bf16 v[108:111], v[130:133], v[170:173], v[108:111]
	v_mfma_f32_16x16x32_bf16 v[104:107], v[138:141], v[170:173], v[104:107]
	v_mfma_f32_16x16x32_bf16 v[92:95], v[130:133], v[178:181], v[92:95]
	v_mfma_f32_16x16x32_bf16 v[88:91], v[138:141], v[178:181], v[88:91]
	v_mfma_f32_16x16x32_bf16 v[76:79], v[130:133], v[186:189], v[76:79]
	v_mfma_f32_16x16x32_bf16 v[72:75], v[138:141], v[186:189], v[72:75]
	v_mfma_f32_16x16x32_bf16 v[126:129], v[134:137], v[166:169], v[126:129]
	v_mfma_f32_16x16x32_bf16 v[122:125], v[142:145], v[166:169], v[122:125]
	v_mfma_f32_16x16x32_bf16 v[108:111], v[134:137], v[174:177], v[108:111]
	v_mfma_f32_16x16x32_bf16 v[104:107], v[142:145], v[174:177], v[104:107]
	v_mfma_f32_16x16x32_bf16 v[92:95], v[134:137], v[182:185], v[92:95]
	v_mfma_f32_16x16x32_bf16 v[88:91], v[142:145], v[182:185], v[88:91]
	v_mfma_f32_16x16x32_bf16 v[76:79], v[134:137], v[190:193], v[76:79]
	v_mfma_f32_16x16x32_bf16 v[72:75], v[142:145], v[190:193], v[72:75]
	v_mfma_f32_16x16x32_bf16 v[118:121], v[146:149], v[162:165], v[118:121]
	v_mfma_f32_16x16x32_bf16 v[114:117], v[154:157], v[162:165], v[114:117]
	v_mfma_f32_16x16x32_bf16 v[100:103], v[146:149], v[170:173], v[100:103]
	v_mfma_f32_16x16x32_bf16 v[96:99], v[154:157], v[170:173], v[96:99]
	v_mfma_f32_16x16x32_bf16 v[84:87], v[146:149], v[178:181], v[84:87]
	v_mfma_f32_16x16x32_bf16 v[80:83], v[154:157], v[178:181], v[80:83]
	v_mfma_f32_16x16x32_bf16 v[68:71], v[146:149], v[186:189], v[68:71]
	v_mfma_f32_16x16x32_bf16 v[64:67], v[154:157], v[186:189], v[64:67]
	v_mfma_f32_16x16x32_bf16 v[118:121], v[150:153], v[166:169], v[118:121]
	v_mfma_f32_16x16x32_bf16 v[114:117], v[158:161], v[166:169], v[114:117]
	v_mfma_f32_16x16x32_bf16 v[100:103], v[150:153], v[174:177], v[100:103]
	v_mfma_f32_16x16x32_bf16 v[96:99], v[158:161], v[174:177], v[96:99]
	v_mfma_f32_16x16x32_bf16 v[84:87], v[150:153], v[182:185], v[84:87]
	v_mfma_f32_16x16x32_bf16 v[80:83], v[158:161], v[182:185], v[80:83]
	v_mfma_f32_16x16x32_bf16 v[68:71], v[150:153], v[190:193], v[68:71]
	v_mfma_f32_16x16x32_bf16 v[64:67], v[158:161], v[190:193], v[64:67]
	s_barrier
	s_add_i32 s56, s56, s40
	v_lshl_add_u64 v[196:197], s[30:31], 0, v[112:113]
	s_mov_b32 m0, s56
	ds_read_b128 v[162:165], v246 offset:16384
	ds_read_b128 v[166:169], v246 offset:17408
	ds_read_b128 v[170:173], v246 offset:18432
	ds_read_b128 v[174:177], v246 offset:19456
	ds_read_b128 v[178:181], v246 offset:20480
	ds_read_b128 v[182:185], v246 offset:21504
	ds_read_b128 v[186:189], v246 offset:22528
	ds_read_b128 v[190:193], v246 offset:23552
	global_load_lds_dwordx4 v[196:197], off
	s_add_i32 m0, s56, 0x2000
	s_add_u32 s56, s30, 0x80000
	v_lshl_add_u64 v[198:199], s[30:31], 0, v[206:207]
	s_addc_u32 s57, s31, 0
	s_add_i32 s58, s58, s40
	global_load_lds_dwordx4 v[198:199], off
	v_lshl_add_u64 v[202:203], s[56:57], 0, v[112:113]
	s_mov_b32 m0, s58
	v_lshl_add_u64 v[204:205], s[34:35], 0, v[206:207]
	global_load_lds_dwordx4 v[202:203], off
	v_lshl_add_u64 v[202:203], s[56:57], 0, v[206:207]
	s_add_i32 m0, s58, 0x2000
	s_nop 0
	global_load_lds_dwordx4 v[202:203], off
	v_lshl_add_u64 v[202:203], s[34:35], 0, v[112:113]
	s_mov_b32 m0, s41
	s_nop 0
	global_load_lds_dwordx4 v[202:203], off
	s_mov_b32 m0, s42
	s_nop 0
	global_load_lds_dwordx4 v[204:205], off
	s_waitcnt vmcnt(8)
	s_waitcnt lgkmcnt(0)
	s_barrier
; #define PG8_STAGE(bufoff, gbase, voff) do { _Pragma("unroll") for (int _i = 0; _i < 2; ++_i) \
;         __builtin_amdgcn_global_load_lds((const unsigned*)((const char*)(gbase) + (voff)[_i]), (PG8_LAS unsigned*)(lds + (bufoff) + ldsw + _i * 8192), 16, 0, 0); } while (0)
; #define PG8_LDA(dst, b, h) do { _Pragma("unroll") for (int m = 0; m < 4; ++m) _Pragma("unroll") for (int k = 0; k < 2; ++k) dst[m][k] = *(const PG8_LAS bf16x8*)(lds + PG8_SA(b, h) + aoff + m * 2048 + k * 1024); } while (0)
; #define PG8_LDB(dst, b, h) do { _Pragma("unroll") for (int n = 0; n < 2; ++n) _Pragma("unroll") for (int k = 0; k < 2; ++k) dst[n][k] = *(const PG8_LAS bf16x8*)(lds + PG8_SB(b, h) + boff + n * 2048 + k * 1024); } while (0)
; #define PG8_MMA(ai, bj, At, Bt) do { __builtin_amdgcn_s_setprio(1); _Pragma("unroll") for (int m = 0; m < 4; ++m) _Pragma("unroll") for (int n = 0; n < 2; ++n) _Pragma("unroll") for (int k = 0; k < 2; ++k) \
;         acc[ai][bj][m][n] = __builtin_amdgcn_mfma_f32_16x16x32_bf16(Bt[n][k], At[m][k], acc[ai][bj][m][n], 0, 0, 0); __builtin_amdgcn_s_setprio(0); } while (0)
; #define PG8_WAIT_V(n) asm volatile("s_waitcnt vmcnt(" #n ")" ::: "memory")
; #define PG8_WAIT_L(n) asm volatile("s_waitcnt lgkmcnt(" #n ")" ::: "memory")
; #define PG8_BAR __builtin_amdgcn_s_barrier()
; #define PG8_SCHED __builtin_amdgcn_sched_barrier(0)
; template <class Epi, class Sched, bool ALIGN_EPI = false, bool SP2 = false>
; __device__ __forceinline__ void gemm_phase(PG8_LAS unsigned char* lds, const Gemm g, const Sched& S, const Epi& E) {
;     ...
;             PG8_WAIT_V(8); PG8_WAIT_L(0); PG8_BAR; PG8_MMA(1, 0, At, B0); PG8_MMA(1, 1, At, B1); PG8_BAR; PG8_SCHED;
;             PG8_LDB(B0, 1, 0); PG8_LDB(B1, 1, 1); PG8_SCHED; PG8_LDA(At, 1, 0); PG8_STAGE(PG8_SA(0, 1), a2 + hstepA, voffA);
;             PG8_WAIT_V(8); PG8_WAIT_L(0); PG8_BAR; PG8_MMA(0, 0, At, B0); PG8_MMA(0, 1, At, B1); PG8_BAR; PG8_SCHED;
;             PG8_LDA(At, 1, 1); PG8_STAGE(PG8_SB(1, 0), b3, voffB); PG8_STAGE(PG8_SB(1, 1), b3 + hstepB, voffB); PG8_STAGE(PG8_SA(1, 0), a3, voffA);
	s_waitcnt lgkmcnt(0)
	v_mfma_f32_16x16x32_bf16 v[60:63], v[130:133], v[162:165], v[60:63]
	v_mfma_f32_16x16x32_bf16 v[56:59], v[138:141], v[162:165], v[56:59]
	v_mfma_f32_16x16x32_bf16 v[44:47], v[130:133], v[170:173], v[44:47]
	v_mfma_f32_16x16x32_bf16 v[40:43], v[138:141], v[170:173], v[40:43]
	v_mfma_f32_16x16x32_bf16 v[28:31], v[130:133], v[178:181], v[28:31]
	v_mfma_f32_16x16x32_bf16 v[24:27], v[138:141], v[178:181], v[24:27]
	v_mfma_f32_16x16x32_bf16 v[12:15], v[130:133], v[186:189], v[12:15]
	v_mfma_f32_16x16x32_bf16 v[8:11], v[138:141], v[186:189], v[8:11]
	v_mfma_f32_16x16x32_bf16 v[60:63], v[134:137], v[166:169], v[60:63]
	v_mfma_f32_16x16x32_bf16 v[56:59], v[142:145], v[166:169], v[56:59]
	v_mfma_f32_16x16x32_bf16 v[44:47], v[134:137], v[174:177], v[44:47]
	v_mfma_f32_16x16x32_bf16 v[40:43], v[142:145], v[174:177], v[40:43]
	v_mfma_f32_16x16x32_bf16 v[28:31], v[134:137], v[182:185], v[28:31]
	v_mfma_f32_16x16x32_bf16 v[24:27], v[142:145], v[182:185], v[24:27]
	v_mfma_f32_16x16x32_bf16 v[12:15], v[134:137], v[190:193], v[12:15]
	v_mfma_f32_16x16x32_bf16 v[8:11], v[142:145], v[190:193], v[8:11]
	v_mfma_f32_16x16x32_bf16 v[52:55], v[146:149], v[162:165], v[52:55]
	v_mfma_f32_16x16x32_bf16 v[48:51], v[154:157], v[162:165], v[48:51]
	v_mfma_f32_16x16x32_bf16 v[36:39], v[146:149], v[170:173], v[36:39]
	v_mfma_f32_16x16x32_bf16 v[32:35], v[154:157], v[170:173], v[32:35]
	v_mfma_f32_16x16x32_bf16 v[20:23], v[146:149], v[178:181], v[20:23]
	v_mfma_f32_16x16x32_bf16 v[16:19], v[154:157], v[178:181], v[16:19]
	v_mfma_f32_16x16x32_bf16 v[4:7], v[146:149], v[186:189], v[4:7]
	v_mfma_f32_16x16x32_bf16 v[0:3], v[154:157], v[186:189], v[0:3]
	v_mfma_f32_16x16x32_bf16 v[52:55], v[150:153], v[166:169], v[52:55]
	v_mfma_f32_16x16x32_bf16 v[48:51], v[158:161], v[166:169], v[48:51]
	v_mfma_f32_16x16x32_bf16 v[36:39], v[150:153], v[174:177], v[36:39]
	v_mfma_f32_16x16x32_bf16 v[32:35], v[158:161], v[174:177], v[32:35]
	v_mfma_f32_16x16x32_bf16 v[20:23], v[150:153], v[182:185], v[20:23]
	v_mfma_f32_16x16x32_bf16 v[16:19], v[158:161], v[182:185], v[16:19]
	v_mfma_f32_16x16x32_bf16 v[4:7], v[150:153], v[190:193], v[4:7]
	v_mfma_f32_16x16x32_bf16 v[0:3], v[158:161], v[190:193], v[0:3]
	s_barrier
	s_add_i32 s56, 0, 0x18000
	s_add_i32 s57, 0, 0x1c000
	v_add_u32_e32 v142, s56, v244
	v_add_u32_e32 v158, s57, v244
	ds_read_b128 v[130:133], v142
	ds_read_b128 v[134:137], v142 offset:1024
	ds_read_b128 v[138:141], v142 offset:2048
	ds_read_b128 v[142:145], v142 offset:3072
	ds_read_b128 v[146:149], v158
	ds_read_b128 v[150:153], v158 offset:1024
	ds_read_b128 v[154:157], v158 offset:2048
	ds_read_b128 v[158:161], v158 offset:3072
	s_add_u32 s34, s34, 0x80000
	s_addc_u32 s35, s35, 0
	s_mov_b32 m0, s43
	v_lshl_add_u64 v[212:213], s[34:35], 0, v[112:113]
	ds_read_b128 v[162:165], v246 offset:32768
	ds_read_b128 v[166:169], v246 offset:33792
	ds_read_b128 v[170:173], v246 offset:34816
	ds_read_b128 v[174:177], v246 offset:35840
	ds_read_b128 v[178:181], v246 offset:36864
	ds_read_b128 v[182:185], v246 offset:37888
	ds_read_b128 v[186:189], v246 offset:38912
	ds_read_b128 v[190:193], v246 offset:39936
	global_load_lds_dwordx4 v[212:213], off
	v_lshl_add_u64 v[212:213], s[34:35], 0, v[206:207]
	s_mov_b32 m0, s44
	s_nop 0
	global_load_lds_dwordx4 v[212:213], off
	s_waitcnt vmcnt(8)
	s_waitcnt lgkmcnt(0)
	s_barrier
	s_waitcnt lgkmcnt(0)
	v_mfma_f32_16x16x32_bf16 v[126:129], v[130:133], v[162:165], v[126:129]
	v_mfma_f32_16x16x32_bf16 v[122:125], v[138:141], v[162:165], v[122:125]
	v_mfma_f32_16x16x32_bf16 v[108:111], v[130:133], v[170:173], v[108:111]
	v_mfma_f32_16x16x32_bf16 v[104:107], v[138:141], v[170:173], v[104:107]
	v_mfma_f32_16x16x32_bf16 v[92:95], v[130:133], v[178:181], v[92:95]
	v_mfma_f32_16x16x32_bf16 v[88:91], v[138:141], v[178:181], v[88:91]
	v_mfma_f32_16x16x32_bf16 v[76:79], v[130:133], v[186:189], v[76:79]
	v_mfma_f32_16x16x32_bf16 v[72:75], v[138:141], v[186:189], v[72:75]
	v_mfma_f32_16x16x32_bf16 v[126:129], v[134:137], v[166:169], v[126:129]
	v_mfma_f32_16x16x32_bf16 v[122:125], v[142:145], v[166:169], v[122:125]
	v_mfma_f32_16x16x32_bf16 v[108:111], v[134:137], v[174:177], v[108:111]
	v_mfma_f32_16x16x32_bf16 v[104:107], v[142:145], v[174:177], v[104:107]
	v_mfma_f32_16x16x32_bf16 v[92:95], v[134:137], v[182:185], v[92:95]
	v_mfma_f32_16x16x32_bf16 v[88:91], v[142:145], v[182:185], v[88:91]
	v_mfma_f32_16x16x32_bf16 v[76:79], v[134:137], v[190:193], v[76:79]
	v_mfma_f32_16x16x32_bf16 v[72:75], v[142:145], v[190:193], v[72:75]
	v_mfma_f32_16x16x32_bf16 v[118:121], v[146:149], v[162:165], v[118:121]
	v_mfma_f32_16x16x32_bf16 v[114:117], v[154:157], v[162:165], v[114:117]
	v_mfma_f32_16x16x32_bf16 v[100:103], v[146:149], v[170:173], v[100:103]
	v_mfma_f32_16x16x32_bf16 v[96:99], v[154:157], v[170:173], v[96:99]
	v_mfma_f32_16x16x32_bf16 v[84:87], v[146:149], v[178:181], v[84:87]
	v_mfma_f32_16x16x32_bf16 v[80:83], v[154:157], v[178:181], v[80:83]
	v_mfma_f32_16x16x32_bf16 v[68:71], v[146:149], v[186:189], v[68:71]
	v_mfma_f32_16x16x32_bf16 v[64:67], v[154:157], v[186:189], v[64:67]
	v_mfma_f32_16x16x32_bf16 v[118:121], v[150:153], v[166:169], v[118:121]
	v_mfma_f32_16x16x32_bf16 v[114:117], v[158:161], v[166:169], v[114:117]
	v_mfma_f32_16x16x32_bf16 v[100:103], v[150:153], v[174:177], v[100:103]
	v_mfma_f32_16x16x32_bf16 v[96:99], v[158:161], v[174:177], v[96:99]
	v_mfma_f32_16x16x32_bf16 v[84:87], v[150:153], v[182:185], v[84:87]
	v_mfma_f32_16x16x32_bf16 v[80:83], v[158:161], v[182:185], v[80:83]
	v_mfma_f32_16x16x32_bf16 v[68:71], v[150:153], v[190:193], v[68:71]
	v_mfma_f32_16x16x32_bf16 v[64:67], v[158:161], v[190:193], v[64:67]
	s_barrier
; #define PG8_STAGE(bufoff, gbase, voff) do { _Pragma("unroll") for (int _i = 0; _i < 2; ++_i) \
;         __builtin_amdgcn_global_load_lds((const unsigned*)((const char*)(gbase) + (voff)[_i]), (PG8_LAS unsigned*)(lds + (bufoff) + ldsw + _i * 8192), 16, 0, 0); } while (0)
; #define PG8_LDA(dst, b, h) do { _Pragma("unroll") for (int m = 0; m < 4; ++m) _Pragma("unroll") for (int k = 0; k < 2; ++k) dst[m][k] = *(const PG8_LAS bf16x8*)(lds + PG8_SA(b, h) + aoff + m * 2048 + k * 1024); } while (0)
; #define PG8_MMA(ai, bj, At, Bt) do { __builtin_amdgcn_s_setprio(1); _Pragma("unroll") for (int m = 0; m < 4; ++m) _Pragma("unroll") for (int n = 0; n < 2; ++n) _Pragma("unroll") for (int k = 0; k < 2; ++k) \
;         acc[ai][bj][m][n] = __builtin_amdgcn_mfma_f32_16x16x32_bf16(Bt[n][k], At[m][k], acc[ai][bj][m][n], 0, 0, 0); __builtin_amdgcn_s_setprio(0); } while (0)
; #define PG8_WAIT_V(n) asm volatile("s_waitcnt vmcnt(" #n ")" ::: "memory")
; #define PG8_WAIT_L(n) asm volatile("s_waitcnt lgkmcnt(" #n ")" ::: "memory")
; #define PG8_BAR __builtin_amdgcn_s_barrier()
; #define PG8_SCHED __builtin_amdgcn_sched_barrier(0)
; template <class Epi, class Sched, bool ALIGN_EPI = false, bool SP2 = false>
; __device__ __forceinline__ void gemm_phase(PG8_LAS unsigned char* lds, const Gemm g, const Sched& S, const Epi& E) {
;     ...
;             PG8_LDA(At, 1, 1); PG8_STAGE(PG8_SB(1, 0), b3, voffB); PG8_STAGE(PG8_SB(1, 1), b3 + hstepB, voffB); PG8_STAGE(PG8_SA(1, 0), a3, voffA);
;             PG8_WAIT_V(8); PG8_WAIT_L(0); PG8_BAR; PG8_MMA(1, 0, At, B0); PG8_MMA(1, 1, At, B1); PG8_BAR; PG8_SCHED;
	s_add_i32 s34, s56, s40
	v_lshl_add_u64 v[196:197], v[196:197], 0, s[2:3]
	s_mov_b32 m0, s34
	ds_read_b128 v[162:165], v246 offset:49152
	ds_read_b128 v[166:169], v246 offset:50176
	ds_read_b128 v[170:173], v246 offset:51200
	ds_read_b128 v[174:177], v246 offset:52224
	ds_read_b128 v[178:181], v246 offset:53248
	ds_read_b128 v[182:185], v246 offset:54272
	ds_read_b128 v[186:189], v246 offset:55296
	ds_read_b128 v[190:193], v246 offset:56320
	global_load_lds_dwordx4 v[196:197], off
	s_add_i32 m0, s34, 0x2000
	s_add_u32 s30, s30, 0x80080
	v_lshl_add_u64 v[196:197], v[198:199], 0, s[2:3]
	s_addc_u32 s31, s31, 0
	s_add_i32 s34, s57, s40
	global_load_lds_dwordx4 v[196:197], off
	v_lshl_add_u64 v[196:197], s[30:31], 0, v[112:113]
	s_mov_b32 m0, s34
	s_nop 0
	global_load_lds_dwordx4 v[196:197], off
	v_lshl_add_u64 v[196:197], s[30:31], 0, v[206:207]
	s_add_i32 m0, s34, 0x2000
	s_nop 0
	global_load_lds_dwordx4 v[196:197], off
	v_lshl_add_u64 v[196:197], v[202:203], 0, s[2:3]
	s_mov_b32 m0, s46
	s_nop 0
	global_load_lds_dwordx4 v[196:197], off
	v_lshl_add_u64 v[196:197], v[204:205], 0, s[2:3]
	s_mov_b32 m0, s47
	s_nop 0
	global_load_lds_dwordx4 v[196:197], off
	s_waitcnt vmcnt(8)
	s_waitcnt lgkmcnt(0)
	s_barrier
	s_waitcnt lgkmcnt(0)
	v_mfma_f32_16x16x32_bf16 v[60:63], v[130:133], v[162:165], v[60:63]
	v_mfma_f32_16x16x32_bf16 v[56:59], v[138:141], v[162:165], v[56:59]
	v_mfma_f32_16x16x32_bf16 v[44:47], v[130:133], v[170:173], v[44:47]
	v_mfma_f32_16x16x32_bf16 v[40:43], v[138:141], v[170:173], v[40:43]
	v_mfma_f32_16x16x32_bf16 v[28:31], v[130:133], v[178:181], v[28:31]
	v_mfma_f32_16x16x32_bf16 v[24:27], v[138:141], v[178:181], v[24:27]
	v_mfma_f32_16x16x32_bf16 v[12:15], v[130:133], v[186:189], v[12:15]
	v_mfma_f32_16x16x32_bf16 v[8:11], v[138:141], v[186:189], v[8:11]
	v_mfma_f32_16x16x32_bf16 v[60:63], v[134:137], v[166:169], v[60:63]
	v_mfma_f32_16x16x32_bf16 v[56:59], v[142:145], v[166:169], v[56:59]
	v_mfma_f32_16x16x32_bf16 v[44:47], v[134:137], v[174:177], v[44:47]
	v_mfma_f32_16x16x32_bf16 v[40:43], v[142:145], v[174:177], v[40:43]
	v_mfma_f32_16x16x32_bf16 v[28:31], v[134:137], v[182:185], v[28:31]
	v_mfma_f32_16x16x32_bf16 v[24:27], v[142:145], v[182:185], v[24:27]
	v_mfma_f32_16x16x32_bf16 v[12:15], v[134:137], v[190:193], v[12:15]
	v_mfma_f32_16x16x32_bf16 v[8:11], v[142:145], v[190:193], v[8:11]
	v_mfma_f32_16x16x32_bf16 v[52:55], v[146:149], v[162:165], v[52:55]
	v_mfma_f32_16x16x32_bf16 v[48:51], v[154:157], v[162:165], v[48:51]
	v_mfma_f32_16x16x32_bf16 v[36:39], v[146:149], v[170:173], v[36:39]
	v_mfma_f32_16x16x32_bf16 v[32:35], v[154:157], v[170:173], v[32:35]
	v_mfma_f32_16x16x32_bf16 v[20:23], v[146:149], v[178:181], v[20:23]
	v_mfma_f32_16x16x32_bf16 v[16:19], v[154:157], v[178:181], v[16:19]
	v_mfma_f32_16x16x32_bf16 v[4:7], v[146:149], v[186:189], v[4:7]
	v_mfma_f32_16x16x32_bf16 v[0:3], v[154:157], v[186:189], v[0:3]
	v_mfma_f32_16x16x32_bf16 v[52:55], v[150:153], v[166:169], v[52:55]
	v_mfma_f32_16x16x32_bf16 v[48:51], v[158:161], v[166:169], v[48:51]
	v_mfma_f32_16x16x32_bf16 v[36:39], v[150:153], v[174:177], v[36:39]
	v_mfma_f32_16x16x32_bf16 v[32:35], v[158:161], v[174:177], v[32:35]
	v_mfma_f32_16x16x32_bf16 v[20:23], v[150:153], v[182:185], v[20:23]
	v_mfma_f32_16x16x32_bf16 v[16:19], v[158:161], v[182:185], v[16:19]
	v_mfma_f32_16x16x32_bf16 v[4:7], v[150:153], v[190:193], v[4:7]
	v_mfma_f32_16x16x32_bf16 v[0:3], v[158:161], v[190:193], v[0:3]
	s_barrier
	s_add_i32 s55, s55, 2
	s_add_u32 s53, s53, 0x100
	s_addc_u32 s54, s54, 0
	s_add_u32 s10, s10, 0x100
	s_addc_u32 s11, s11, 0
	s_cmp_gt_u32 s55, 29
	s_cbranch_scc0 .LBB0_591
	s_and_b64 vcc, exec, s[20:21]
	s_cbranch_vccz .LBB0_594
	s_barrier

; #define PG8_STAGE(bufoff, gbase, voff) do { _Pragma("unroll") for (int _i = 0; _i < 2; ++_i) \
;         __builtin_amdgcn_global_load_lds((const unsigned*)((const char*)(gbase) + (voff)[_i]), (PG8_LAS unsigned*)(lds + (bufoff) + ldsw + _i * 8192), 16, 0, 0); } while (0)
; #define PG8_LDA(dst, b, h) do { _Pragma("unroll") for (int m = 0; m < 4; ++m) _Pragma("unroll") for (int k = 0; k < 2; ++k) dst[m][k] = *(const PG8_LAS bf16x8*)(lds + PG8_SA(b, h) + aoff + m * 2048 + k * 1024); } while (0)
; #define PG8_LDB(dst, b, h) do { _Pragma("unroll") for (int n = 0; n < 2; ++n) _Pragma("unroll") for (int k = 0; k < 2; ++k) dst[n][k] = *(const PG8_LAS bf16x8*)(lds + PG8_SB(b, h) + boff + n * 2048 + k * 1024); } while (0)
; #define PG8_MMA(ai, bj, At, Bt) do { __builtin_amdgcn_s_setprio(1); _Pragma("unroll") for (int m = 0; m < 4; ++m) _Pragma("unroll") for (int n = 0; n < 2; ++n) _Pragma("unroll") for (int k = 0; k < 2; ++k) \
;         acc[ai][bj][m][n] = __builtin_amdgcn_mfma_f32_16x16x32_bf16(Bt[n][k], At[m][k], acc[ai][bj][m][n], 0, 0, 0); __builtin_amdgcn_s_setprio(0); } while (0)
; #define PG8_WAIT_V(n) asm volatile("s_waitcnt vmcnt(" #n ")" ::: "memory")
; #define PG8_WAIT_L(n) asm volatile("s_waitcnt lgkmcnt(" #n ")" ::: "memory")
; #define PG8_BAR __builtin_amdgcn_s_barrier()
; template <class Epi, class Sched, bool ALIGN_EPI = false, bool SP2 = false>
; __device__ __forceinline__ void gemm_phase(PG8_LAS unsigned char* lds, const Gemm g, const Sched& S, const Epi& E) {
;     ...
;             const char* a1 = cA + (size_t)(t + 1) * kstep;
;             const char* a2 = last ? nA : cA + (size_t)(t + 2) * kstep; const char* b2 = last ? nB : cB + (size_t)(t + 2) * kstep;
;             const char* a3 = a2 + kstep; const char* b3 = b2 + kstep;
;             if (last && has_next) S.a_ready(nxt);
;             if constexpr (SP2) {
;             PG8_LDB(B0, 0, 0); PG8_LDB(B1, 0, 1); PG8_SCHED; PG8_LDA(At, 0, 0); PG8_STAGE(PG8_SA(1, 1), a1 + hstepA, voffA);
;             PG8_WAIT_V(8); PG8_WAIT_L(0); PG8_BAR; PG8_MMA(0, 0, At, B0); PG8_MMA(0, 1, At, B1); PG8_BAR; PG8_SCHED;
;             PG8_LDA(At, 0, 1); PG8_STAGE(PG8_SB(0, 0), b2, voffB); PG8_STAGE(PG8_SB(0, 1), b2 + hstepB, voffB); PG8_STAGE(PG8_SA(0, 0), a2, voffA);
;             PG8_WAIT_V(8); PG8_WAIT_L(0); PG8_BAR; PG8_MMA(1, 0, At, B0); PG8_MMA(1, 1, At, B1); PG8_BAR; PG8_SCHED;
.LBB0_722:
	s_add_u32 s26, s24, 0xfff80080
	s_addc_u32 s27, s25, -1
	s_add_i32 s49, 0, 0x10000
	s_cmp_eq_u32 s48, 28
	s_cselect_b32 s29, s19, s27
	s_cselect_b32 s28, s44, s26
	v_add_u32_e32 v136, s49, v139
	s_cselect_b32 s27, s17, s47
	s_cselect_b32 s26, s45, s46
	s_add_i32 s52, 0, 0x14000
	ds_read_b128 v[142:145], v136
	ds_read_b128 v[146:149], v136 offset:1024
	ds_read_b128 v[150:153], v136 offset:2048
	ds_read_b128 v[154:157], v136 offset:3072
	v_add_u32_e32 v136, s52, v139
	ds_read_b128 v[158:161], v136
	ds_read_b128 v[162:165], v136 offset:1024
	ds_read_b128 v[166:169], v136 offset:2048
	ds_read_b128 v[170:173], v136 offset:3072
	v_lshl_add_u64 v[136:137], s[24:25], 0, v[134:135]
	s_add_i32 m0, s35, 0xc000
	ds_read_b128 v[174:177], v141
	ds_read_b128 v[178:181], v141 offset:1024
	ds_read_b128 v[182:185], v141 offset:2048
	ds_read_b128 v[186:189], v141 offset:3072
	ds_read_b128 v[190:193], v141 offset:4096
	ds_read_b128 v[196:199], v141 offset:5120
	ds_read_b128 v[202:205], v141 offset:6144
	ds_read_b128 v[206:209], v141 offset:7168
	global_load_lds_dwordx4 v[136:137], off
	v_lshl_add_u64 v[136:137], s[24:25], 0, v[132:133]
	s_add_i32 m0, s35, 0xe000
	s_nop 0
	global_load_lds_dwordx4 v[136:137], off
	s_waitcnt vmcnt(8)
	s_waitcnt lgkmcnt(0)
	s_barrier
	s_waitcnt lgkmcnt(0)
	v_mfma_f32_16x16x32_bf16 v[126:129], v[142:145], v[174:177], v[126:129]
	v_mfma_f32_16x16x32_bf16 v[122:125], v[150:153], v[174:177], v[122:125]
	v_mfma_f32_16x16x32_bf16 v[108:111], v[142:145], v[182:185], v[108:111]
	v_mfma_f32_16x16x32_bf16 v[104:107], v[150:153], v[182:185], v[104:107]
	v_mfma_f32_16x16x32_bf16 v[92:95], v[142:145], v[190:193], v[92:95]
	v_mfma_f32_16x16x32_bf16 v[88:91], v[150:153], v[190:193], v[88:91]
	v_mfma_f32_16x16x32_bf16 v[76:79], v[142:145], v[202:205], v[76:79]
	v_mfma_f32_16x16x32_bf16 v[72:75], v[150:153], v[202:205], v[72:75]
	v_mfma_f32_16x16x32_bf16 v[126:129], v[146:149], v[178:181], v[126:129]
	v_mfma_f32_16x16x32_bf16 v[122:125], v[154:157], v[178:181], v[122:125]
	v_mfma_f32_16x16x32_bf16 v[108:111], v[146:149], v[186:189], v[108:111]
	v_mfma_f32_16x16x32_bf16 v[104:107], v[154:157], v[186:189], v[104:107]
	v_mfma_f32_16x16x32_bf16 v[92:95], v[146:149], v[196:199], v[92:95]
	v_mfma_f32_16x16x32_bf16 v[88:91], v[154:157], v[196:199], v[88:91]
	v_mfma_f32_16x16x32_bf16 v[76:79], v[146:149], v[206:209], v[76:79]
	v_mfma_f32_16x16x32_bf16 v[72:75], v[154:157], v[206:209], v[72:75]
	v_mfma_f32_16x16x32_bf16 v[118:121], v[158:161], v[174:177], v[118:121]
	v_mfma_f32_16x16x32_bf16 v[114:117], v[166:169], v[174:177], v[114:117]
	v_mfma_f32_16x16x32_bf16 v[100:103], v[158:161], v[182:185], v[100:103]
	v_mfma_f32_16x16x32_bf16 v[96:99], v[166:169], v[182:185], v[96:99]
	v_mfma_f32_16x16x32_bf16 v[84:87], v[158:161], v[190:193], v[84:87]
	v_mfma_f32_16x16x32_bf16 v[80:83], v[166:169], v[190:193], v[80:83]
	v_mfma_f32_16x16x32_bf16 v[68:71], v[158:161], v[202:205], v[68:71]
	v_mfma_f32_16x16x32_bf16 v[64:67], v[166:169], v[202:205], v[64:67]
	v_mfma_f32_16x16x32_bf16 v[118:121], v[162:165], v[178:181], v[118:121]
	v_mfma_f32_16x16x32_bf16 v[114:117], v[170:173], v[178:181], v[114:117]
	v_mfma_f32_16x16x32_bf16 v[100:103], v[162:165], v[186:189], v[100:103]
	v_mfma_f32_16x16x32_bf16 v[96:99], v[170:173], v[186:189], v[96:99]
	v_mfma_f32_16x16x32_bf16 v[84:87], v[162:165], v[196:199], v[84:87]
	v_mfma_f32_16x16x32_bf16 v[80:83], v[170:173], v[196:199], v[80:83]
	v_mfma_f32_16x16x32_bf16 v[68:71], v[162:165], v[206:209], v[68:71]
	v_mfma_f32_16x16x32_bf16 v[64:67], v[170:173], v[206:209], v[64:67]
	s_barrier
	s_add_i32 s49, s49, s34
	v_lshl_add_u64 v[136:137], s[26:27], 0, v[112:113]
	s_mov_b32 m0, s49
	ds_read_b128 v[174:177], v141 offset:16384
	ds_read_b128 v[178:181], v141 offset:17408
	ds_read_b128 v[182:185], v141 offset:18432
	ds_read_b128 v[186:189], v141 offset:19456
	ds_read_b128 v[190:193], v141 offset:20480
	ds_read_b128 v[196:199], v141 offset:21504
	ds_read_b128 v[202:205], v141 offset:22528
	ds_read_b128 v[206:209], v141 offset:23552
	global_load_lds_dwordx4 v[136:137], off
	s_add_i32 m0, s49, 0x2000
	s_add_u32 s50, s26, 0x80000
	v_lshl_add_u64 v[210:211], s[26:27], 0, v[130:131]
	s_addc_u32 s51, s27, 0
	s_add_i32 s49, s52, s34
	global_load_lds_dwordx4 v[210:211], off
	v_lshl_add_u64 v[212:213], s[50:51], 0, v[112:113]
	s_mov_b32 m0, s49
	v_lshl_add_u64 v[214:215], s[28:29], 0, v[130:131]
	global_load_lds_dwordx4 v[212:213], off
	v_lshl_add_u64 v[212:213], s[50:51], 0, v[130:131]
	s_add_i32 m0, s49, 0x2000
	s_nop 0
	global_load_lds_dwordx4 v[212:213], off
	v_lshl_add_u64 v[212:213], s[28:29], 0, v[112:113]
	s_mov_b32 m0, s35
	s_nop 0
	global_load_lds_dwordx4 v[212:213], off
	s_mov_b32 m0, s36
	s_nop 0
	global_load_lds_dwordx4 v[214:215], off
	s_waitcnt vmcnt(8)
	s_waitcnt lgkmcnt(0)
	s_barrier
; #define PG8_STAGE(bufoff, gbase, voff) do { _Pragma("unroll") for (int _i = 0; _i < 2; ++_i) \
;         __builtin_amdgcn_global_load_lds((const unsigned*)((const char*)(gbase) + (voff)[_i]), (PG8_LAS unsigned*)(lds + (bufoff) + ldsw + _i * 8192), 16, 0, 0); } while (0)
; #define PG8_LDA(dst, b, h) do { _Pragma("unroll") for (int m = 0; m < 4; ++m) _Pragma("unroll") for (int k = 0; k < 2; ++k) dst[m][k] = *(const PG8_LAS bf16x8*)(lds + PG8_SA(b, h) + aoff + m * 2048 + k * 1024); } while (0)
; #define PG8_LDB(dst, b, h) do { _Pragma("unroll") for (int n = 0; n < 2; ++n) _Pragma("unroll") for (int k = 0; k < 2; ++k) dst[n][k] = *(const PG8_LAS bf16x8*)(lds + PG8_SB(b, h) + boff + n * 2048 + k * 1024); } while (0)
; #define PG8_MMA(ai, bj, At, Bt) do { __builtin_amdgcn_s_setprio(1); _Pragma("unroll") for (int m = 0; m < 4; ++m) _Pragma("unroll") for (int n = 0; n < 2; ++n) _Pragma("unroll") for (int k = 0; k < 2; ++k) \
;         acc[ai][bj][m][n] = __builtin_amdgcn_mfma_f32_16x16x32_bf16(Bt[n][k], At[m][k], acc[ai][bj][m][n], 0, 0, 0); __builtin_amdgcn_s_setprio(0); } while (0)
; #define PG8_WAIT_V(n) asm volatile("s_waitcnt vmcnt(" #n ")" ::: "memory")
; #define PG8_WAIT_L(n) asm volatile("s_waitcnt lgkmcnt(" #n ")" ::: "memory")
; #define PG8_BAR __builtin_amdgcn_s_barrier()
; #define PG8_SCHED __builtin_amdgcn_sched_barrier(0)
; template <class Epi, class Sched, bool ALIGN_EPI = false, bool SP2 = false>
; __device__ __forceinline__ void gemm_phase(PG8_LAS unsigned char* lds, const Gemm g, const Sched& S, const Epi& E) {
;     ...
;             PG8_WAIT_V(8); PG8_WAIT_L(0); PG8_BAR; PG8_MMA(1, 0, At, B0); PG8_MMA(1, 1, At, B1); PG8_BAR; PG8_SCHED;
;             PG8_LDB(B0, 1, 0); PG8_LDB(B1, 1, 1); PG8_SCHED; PG8_LDA(At, 1, 0); PG8_STAGE(PG8_SA(0, 1), a2 + hstepA, voffA);
;             PG8_WAIT_V(8); PG8_WAIT_L(0); PG8_BAR; PG8_MMA(0, 0, At, B0); PG8_MMA(0, 1, At, B1); PG8_BAR; PG8_SCHED;
;             PG8_LDA(At, 1, 1); PG8_STAGE(PG8_SB(1, 0), b3, voffB); PG8_STAGE(PG8_SB(1, 1), b3 + hstepB, voffB); PG8_STAGE(PG8_SA(1, 0), a3, voffA);
	s_waitcnt lgkmcnt(0)
	v_mfma_f32_16x16x32_bf16 v[60:63], v[142:145], v[174:177], v[60:63]
	v_mfma_f32_16x16x32_bf16 v[56:59], v[150:153], v[174:177], v[56:59]
	v_mfma_f32_16x16x32_bf16 v[44:47], v[142:145], v[182:185], v[44:47]
	v_mfma_f32_16x16x32_bf16 v[40:43], v[150:153], v[182:185], v[40:43]
	v_mfma_f32_16x16x32_bf16 v[28:31], v[142:145], v[190:193], v[28:31]
	v_mfma_f32_16x16x32_bf16 v[24:27], v[150:153], v[190:193], v[24:27]
	v_mfma_f32_16x16x32_bf16 v[12:15], v[142:145], v[202:205], v[12:15]
	v_mfma_f32_16x16x32_bf16 v[8:11], v[150:153], v[202:205], v[8:11]
	v_mfma_f32_16x16x32_bf16 v[60:63], v[146:149], v[178:181], v[60:63]
	v_mfma_f32_16x16x32_bf16 v[56:59], v[154:157], v[178:181], v[56:59]
	v_mfma_f32_16x16x32_bf16 v[44:47], v[146:149], v[186:189], v[44:47]
	v_mfma_f32_16x16x32_bf16 v[40:43], v[154:157], v[186:189], v[40:43]
	v_mfma_f32_16x16x32_bf16 v[28:31], v[146:149], v[196:199], v[28:31]
	v_mfma_f32_16x16x32_bf16 v[24:27], v[154:157], v[196:199], v[24:27]
	v_mfma_f32_16x16x32_bf16 v[12:15], v[146:149], v[206:209], v[12:15]
	v_mfma_f32_16x16x32_bf16 v[8:11], v[154:157], v[206:209], v[8:11]
	v_mfma_f32_16x16x32_bf16 v[52:55], v[158:161], v[174:177], v[52:55]
	v_mfma_f32_16x16x32_bf16 v[48:51], v[166:169], v[174:177], v[48:51]
	v_mfma_f32_16x16x32_bf16 v[36:39], v[158:161], v[182:185], v[36:39]
	v_mfma_f32_16x16x32_bf16 v[32:35], v[166:169], v[182:185], v[32:35]
	v_mfma_f32_16x16x32_bf16 v[20:23], v[158:161], v[190:193], v[20:23]
	v_mfma_f32_16x16x32_bf16 v[16:19], v[166:169], v[190:193], v[16:19]
	v_mfma_f32_16x16x32_bf16 v[4:7], v[158:161], v[202:205], v[4:7]
	v_mfma_f32_16x16x32_bf16 v[0:3], v[166:169], v[202:205], v[0:3]
	v_mfma_f32_16x16x32_bf16 v[52:55], v[162:165], v[178:181], v[52:55]
	v_mfma_f32_16x16x32_bf16 v[48:51], v[170:173], v[178:181], v[48:51]
	v_mfma_f32_16x16x32_bf16 v[36:39], v[162:165], v[186:189], v[36:39]
	v_mfma_f32_16x16x32_bf16 v[32:35], v[170:173], v[186:189], v[32:35]
	v_mfma_f32_16x16x32_bf16 v[20:23], v[162:165], v[196:199], v[20:23]
	v_mfma_f32_16x16x32_bf16 v[16:19], v[170:173], v[196:199], v[16:19]
	v_mfma_f32_16x16x32_bf16 v[4:7], v[162:165], v[206:209], v[4:7]
	v_mfma_f32_16x16x32_bf16 v[0:3], v[170:173], v[206:209], v[0:3]
	s_barrier
	s_add_i32 s49, 0, 0x18000
	s_add_i32 s50, 0, 0x1c000
	v_add_u32_e32 v154, s49, v139
	v_add_u32_e32 v170, s50, v139
	ds_read_b128 v[142:145], v154
	ds_read_b128 v[146:149], v154 offset:1024
	ds_read_b128 v[150:153], v154 offset:2048
	ds_read_b128 v[154:157], v154 offset:3072
	ds_read_b128 v[158:161], v170
	ds_read_b128 v[162:165], v170 offset:1024
	ds_read_b128 v[166:169], v170 offset:2048
	ds_read_b128 v[170:173], v170 offset:3072
	s_add_u32 s28, s28, 0x80000
	s_addc_u32 s29, s29, 0
	s_mov_b32 m0, s37
	v_lshl_add_u64 v[216:217], s[28:29], 0, v[112:113]
	ds_read_b128 v[174:177], v141 offset:32768
	ds_read_b128 v[178:181], v141 offset:33792
	ds_read_b128 v[182:185], v141 offset:34816
	ds_read_b128 v[186:189], v141 offset:35840
	ds_read_b128 v[190:193], v141 offset:36864
	ds_read_b128 v[196:199], v141 offset:37888
	ds_read_b128 v[202:205], v141 offset:38912
	ds_read_b128 v[206:209], v141 offset:39936
	global_load_lds_dwordx4 v[216:217], off
	v_lshl_add_u64 v[216:217], s[28:29], 0, v[130:131]
	s_mov_b32 m0, s38
	s_nop 0
	global_load_lds_dwordx4 v[216:217], off
	s_waitcnt vmcnt(8)
	s_waitcnt lgkmcnt(0)
	s_barrier
	s_waitcnt lgkmcnt(0)
	v_mfma_f32_16x16x32_bf16 v[126:129], v[142:145], v[174:177], v[126:129]
	v_mfma_f32_16x16x32_bf16 v[122:125], v[150:153], v[174:177], v[122:125]
	v_mfma_f32_16x16x32_bf16 v[108:111], v[142:145], v[182:185], v[108:111]
	v_mfma_f32_16x16x32_bf16 v[104:107], v[150:153], v[182:185], v[104:107]
	v_mfma_f32_16x16x32_bf16 v[92:95], v[142:145], v[190:193], v[92:95]
	v_mfma_f32_16x16x32_bf16 v[88:91], v[150:153], v[190:193], v[88:91]
	v_mfma_f32_16x16x32_bf16 v[76:79], v[142:145], v[202:205], v[76:79]
	v_mfma_f32_16x16x32_bf16 v[72:75], v[150:153], v[202:205], v[72:75]
	v_mfma_f32_16x16x32_bf16 v[126:129], v[146:149], v[178:181], v[126:129]
	v_mfma_f32_16x16x32_bf16 v[122:125], v[154:157], v[178:181], v[122:125]
	v_mfma_f32_16x16x32_bf16 v[108:111], v[146:149], v[186:189], v[108:111]
	v_mfma_f32_16x16x32_bf16 v[104:107], v[154:157], v[186:189], v[104:107]
	v_mfma_f32_16x16x32_bf16 v[92:95], v[146:149], v[196:199], v[92:95]
	v_mfma_f32_16x16x32_bf16 v[88:91], v[154:157], v[196:199], v[88:91]
	v_mfma_f32_16x16x32_bf16 v[76:79], v[146:149], v[206:209], v[76:79]
	v_mfma_f32_16x16x32_bf16 v[72:75], v[154:157], v[206:209], v[72:75]
	v_mfma_f32_16x16x32_bf16 v[118:121], v[158:161], v[174:177], v[118:121]
	v_mfma_f32_16x16x32_bf16 v[114:117], v[166:169], v[174:177], v[114:117]
	v_mfma_f32_16x16x32_bf16 v[100:103], v[158:161], v[182:185], v[100:103]
	v_mfma_f32_16x16x32_bf16 v[96:99], v[166:169], v[182:185], v[96:99]
	v_mfma_f32_16x16x32_bf16 v[84:87], v[158:161], v[190:193], v[84:87]
	v_mfma_f32_16x16x32_bf16 v[80:83], v[166:169], v[190:193], v[80:83]
	v_mfma_f32_16x16x32_bf16 v[68:71], v[158:161], v[202:205], v[68:71]
	v_mfma_f32_16x16x32_bf16 v[64:67], v[166:169], v[202:205], v[64:67]
	v_mfma_f32_16x16x32_bf16 v[118:121], v[162:165], v[178:181], v[118:121]
	v_mfma_f32_16x16x32_bf16 v[114:117], v[170:173], v[178:181], v[114:117]
	v_mfma_f32_16x16x32_bf16 v[100:103], v[162:165], v[186:189], v[100:103]
	v_mfma_f32_16x16x32_bf16 v[96:99], v[170:173], v[186:189], v[96:99]
	v_mfma_f32_16x16x32_bf16 v[84:87], v[162:165], v[196:199], v[84:87]
	v_mfma_f32_16x16x32_bf16 v[80:83], v[170:173], v[196:199], v[80:83]
	v_mfma_f32_16x16x32_bf16 v[68:71], v[162:165], v[206:209], v[68:71]
	v_mfma_f32_16x16x32_bf16 v[64:67], v[170:173], v[206:209], v[64:67]
	s_barrier
; #define PG8_STAGE(bufoff, gbase, voff) do { _Pragma("unroll") for (int _i = 0; _i < 2; ++_i) \
;         __builtin_amdgcn_global_load_lds((const unsigned*)((const char*)(gbase) + (voff)[_i]), (PG8_LAS unsigned*)(lds + (bufoff) + ldsw + _i * 8192), 16, 0, 0); } while (0)
; #define PG8_LDA(dst, b, h) do { _Pragma("unroll") for (int m = 0; m < 4; ++m) _Pragma("unroll") for (int k = 0; k < 2; ++k) dst[m][k] = *(const PG8_LAS bf16x8*)(lds + PG8_SA(b, h) + aoff + m * 2048 + k * 1024); } while (0)
; #define PG8_MMA(ai, bj, At, Bt) do { __builtin_amdgcn_s_setprio(1); _Pragma("unroll") for (int m = 0; m < 4; ++m) _Pragma("unroll") for (int n = 0; n < 2; ++n) _Pragma("unroll") for (int k = 0; k < 2; ++k) \
;         acc[ai][bj][m][n] = __builtin_amdgcn_mfma_f32_16x16x32_bf16(Bt[n][k], At[m][k], acc[ai][bj][m][n], 0, 0, 0); __builtin_amdgcn_s_setprio(0); } while (0)
; #define PG8_WAIT_V(n) asm volatile("s_waitcnt vmcnt(" #n ")" ::: "memory")
; #define PG8_WAIT_L(n) asm volatile("s_waitcnt lgkmcnt(" #n ")" ::: "memory")
; #define PG8_BAR __builtin_amdgcn_s_barrier()
; #define PG8_SCHED __builtin_amdgcn_sched_barrier(0)
; template <class Epi, class Sched, bool ALIGN_EPI = false, bool SP2 = false>
; __device__ __forceinline__ void gemm_phase(PG8_LAS unsigned char* lds, const Gemm g, const Sched& S, const Epi& E) {
;     ...
;             PG8_LDA(At, 1, 1); PG8_STAGE(PG8_SB(1, 0), b3, voffB); PG8_STAGE(PG8_SB(1, 1), b3 + hstepB, voffB); PG8_STAGE(PG8_SA(1, 0), a3, voffA);
;             PG8_WAIT_V(8); PG8_WAIT_L(0); PG8_BAR; PG8_MMA(1, 0, At, B0); PG8_MMA(1, 1, At, B1); PG8_BAR; PG8_SCHED;
	s_add_i32 s28, s49, s34
	v_lshl_add_u64 v[136:137], v[136:137], 0, s[2:3]
	s_mov_b32 m0, s28
	ds_read_b128 v[174:177], v141 offset:49152
	ds_read_b128 v[178:181], v141 offset:50176
	ds_read_b128 v[182:185], v141 offset:51200
	ds_read_b128 v[186:189], v141 offset:52224
	ds_read_b128 v[190:193], v141 offset:53248
	ds_read_b128 v[196:199], v141 offset:54272
	ds_read_b128 v[202:205], v141 offset:55296
	ds_read_b128 v[206:209], v141 offset:56320
	global_load_lds_dwordx4 v[136:137], off
	s_add_i32 m0, s28, 0x2000
	s_add_u32 s26, s26, 0x80080
	v_lshl_add_u64 v[136:137], v[210:211], 0, s[2:3]
	s_addc_u32 s27, s27, 0
	s_add_i32 s28, s50, s34
	global_load_lds_dwordx4 v[136:137], off
	v_lshl_add_u64 v[136:137], s[26:27], 0, v[112:113]
	s_mov_b32 m0, s28
	s_nop 0
	global_load_lds_dwordx4 v[136:137], off
	v_lshl_add_u64 v[136:137], s[26:27], 0, v[130:131]
	s_add_i32 m0, s28, 0x2000
	s_nop 0
	global_load_lds_dwordx4 v[136:137], off
	v_lshl_add_u64 v[136:137], v[212:213], 0, s[2:3]
	s_mov_b32 m0, s39
	s_nop 0
	global_load_lds_dwordx4 v[136:137], off
	v_lshl_add_u64 v[136:137], v[214:215], 0, s[2:3]
	s_mov_b32 m0, s40
	s_nop 0
	global_load_lds_dwordx4 v[136:137], off
	s_waitcnt vmcnt(8)
	s_waitcnt lgkmcnt(0)
	s_barrier
	s_waitcnt lgkmcnt(0)
	v_mfma_f32_16x16x32_bf16 v[60:63], v[142:145], v[174:177], v[60:63]
	v_mfma_f32_16x16x32_bf16 v[56:59], v[150:153], v[174:177], v[56:59]
	v_mfma_f32_16x16x32_bf16 v[44:47], v[142:145], v[182:185], v[44:47]
	v_mfma_f32_16x16x32_bf16 v[40:43], v[150:153], v[182:185], v[40:43]
	v_mfma_f32_16x16x32_bf16 v[28:31], v[142:145], v[190:193], v[28:31]
	v_mfma_f32_16x16x32_bf16 v[24:27], v[150:153], v[190:193], v[24:27]
	v_mfma_f32_16x16x32_bf16 v[12:15], v[142:145], v[202:205], v[12:15]
	v_mfma_f32_16x16x32_bf16 v[8:11], v[150:153], v[202:205], v[8:11]
	v_mfma_f32_16x16x32_bf16 v[60:63], v[146:149], v[178:181], v[60:63]
	v_mfma_f32_16x16x32_bf16 v[56:59], v[154:157], v[178:181], v[56:59]
	v_mfma_f32_16x16x32_bf16 v[44:47], v[146:149], v[186:189], v[44:47]
	v_mfma_f32_16x16x32_bf16 v[40:43], v[154:157], v[186:189], v[40:43]
	v_mfma_f32_16x16x32_bf16 v[28:31], v[146:149], v[196:199], v[28:31]
	v_mfma_f32_16x16x32_bf16 v[24:27], v[154:157], v[196:199], v[24:27]
	v_mfma_f32_16x16x32_bf16 v[12:15], v[146:149], v[206:209], v[12:15]
	v_mfma_f32_16x16x32_bf16 v[8:11], v[154:157], v[206:209], v[8:11]
	v_mfma_f32_16x16x32_bf16 v[52:55], v[158:161], v[174:177], v[52:55]
	v_mfma_f32_16x16x32_bf16 v[48:51], v[166:169], v[174:177], v[48:51]
	v_mfma_f32_16x16x32_bf16 v[36:39], v[158:161], v[182:185], v[36:39]
	v_mfma_f32_16x16x32_bf16 v[32:35], v[166:169], v[182:185], v[32:35]
	v_mfma_f32_16x16x32_bf16 v[20:23], v[158:161], v[190:193], v[20:23]
	v_mfma_f32_16x16x32_bf16 v[16:19], v[166:169], v[190:193], v[16:19]
	v_mfma_f32_16x16x32_bf16 v[4:7], v[158:161], v[202:205], v[4:7]
	v_mfma_f32_16x16x32_bf16 v[0:3], v[166:169], v[202:205], v[0:3]
	v_mfma_f32_16x16x32_bf16 v[52:55], v[162:165], v[178:181], v[52:55]
	v_mfma_f32_16x16x32_bf16 v[48:51], v[170:173], v[178:181], v[48:51]
	v_mfma_f32_16x16x32_bf16 v[36:39], v[162:165], v[186:189], v[36:39]
	v_mfma_f32_16x16x32_bf16 v[32:35], v[170:173], v[186:189], v[32:35]
	v_mfma_f32_16x16x32_bf16 v[20:23], v[162:165], v[196:199], v[20:23]
	v_mfma_f32_16x16x32_bf16 v[16:19], v[170:173], v[196:199], v[16:19]
	v_mfma_f32_16x16x32_bf16 v[4:7], v[162:165], v[206:209], v[4:7]
	v_mfma_f32_16x16x32_bf16 v[0:3], v[170:173], v[206:209], v[0:3]
	s_barrier
	s_add_i32 s48, s48, 2
	s_add_u32 s46, s46, 0x100
	s_addc_u32 s47, s47, 0
	s_add_u32 s24, s24, 0x100
	s_addc_u32 s25, s25, 0
	s_cmp_gt_u32 s48, 29
	s_cbranch_scc0 .LBB0_722
	s_and_b64 vcc, exec, s[14:15]
	s_cbranch_vccz .LBB0_725
	s_barrier

; #define PG8_STAGE(bufoff, gbase, voff) do { _Pragma("unroll") for (int _i = 0; _i < 2; ++_i) \
;         __builtin_amdgcn_global_load_lds((const unsigned*)((const char*)(gbase) + (voff)[_i]), (PG8_LAS unsigned*)(lds + (bufoff) + ldsw + _i * 8192), 16, 0, 0); } while (0)
; #define PG8_LDA(dst, b, h) do { _Pragma("unroll") for (int m = 0; m < 4; ++m) _Pragma("unroll") for (int k = 0; k < 2; ++k) dst[m][k] = *(const PG8_LAS bf16x8*)(lds + PG8_SA(b, h) + aoff + m * 2048 + k * 1024); } while (0)
; #define PG8_LDB(dst, b, h) do { _Pragma("unroll") for (int n = 0; n < 2; ++n) _Pragma("unroll") for (int k = 0; k < 2; ++k) dst[n][k] = *(const PG8_LAS bf16x8*)(lds + PG8_SB(b, h) + boff + n * 2048 + k * 1024); } while (0)
; #define PG8_MMA(ai, bj, At, Bt) do { __builtin_amdgcn_s_setprio(1); _Pragma("unroll") for (int m = 0; m < 4; ++m) _Pragma("unroll") for (int n = 0; n < 2; ++n) _Pragma("unroll") for (int k = 0; k < 2; ++k) \
;         acc[ai][bj][m][n] = __builtin_amdgcn_mfma_f32_16x16x32_bf16(Bt[n][k], At[m][k], acc[ai][bj][m][n], 0, 0, 0); __builtin_amdgcn_s_setprio(0); } while (0)
; #define PG8_WAIT_V(n) asm volatile("s_waitcnt vmcnt(" #n ")" ::: "memory")
; #define PG8_WAIT_L(n) asm volatile("s_waitcnt lgkmcnt(" #n ")" ::: "memory")
; #define PG8_BAR __builtin_amdgcn_s_barrier()
; template <class Epi, class Sched, bool ALIGN_EPI = false, bool SP2 = false>
; __device__ __forceinline__ void gemm_phase(PG8_LAS unsigned char* lds, const Gemm g, const Sched& S, const Epi& E) {
;     ...
;             const char* a1 = cA + (size_t)(t + 1) * kstep;
;             const char* a2 = last ? nA : cA + (size_t)(t + 2) * kstep; const char* b2 = last ? nB : cB + (size_t)(t + 2) * kstep;
;             const char* a3 = a2 + kstep; const char* b3 = b2 + kstep;
;             if (last && has_next) S.a_ready(nxt);
;             if constexpr (SP2) {
;             PG8_LDB(B0, 0, 0); PG8_LDB(B1, 0, 1); PG8_SCHED; PG8_LDA(At, 0, 0); PG8_STAGE(PG8_SA(1, 1), a1 + hstepA, voffA);
;             PG8_WAIT_V(8); PG8_WAIT_L(0); PG8_BAR; PG8_MMA(0, 0, At, B0); PG8_MMA(0, 1, At, B1); PG8_BAR; PG8_SCHED;
;             PG8_LDA(At, 0, 1); PG8_STAGE(PG8_SB(0, 0), b2, voffB); PG8_STAGE(PG8_SB(0, 1), b2 + hstepB, voffB); PG8_STAGE(PG8_SA(0, 0), a2, voffA);
;             PG8_WAIT_V(8); PG8_WAIT_L(0); PG8_BAR; PG8_MMA(1, 0, At, B0); PG8_MMA(1, 1, At, B1); PG8_BAR; PG8_SCHED;
.LBB0_792:
	s_add_u32 s24, s22, 0x100
	s_addc_u32 s25, s23, 0
	s_add_i32 s52, 0, 0x10000
	s_cmpk_eq_i32 s51, 0x54
	s_cselect_b32 s29, s9, s25
	s_cselect_b32 s28, s8, s24
	s_cselect_b32 s27, s21, s50
	s_cselect_b32 s26, s20, s49
	s_add_i32 s53, 0, 0x14000
	v_add_u32_e32 v148, s52, v207
	v_add_u32_e32 v164, s53, v207
	ds_read_b128 v[136:139], v148
	ds_read_b128 v[140:143], v148 offset:1024
	ds_read_b128 v[144:147], v148 offset:2048
	ds_read_b128 v[148:151], v148 offset:3072
	ds_read_b128 v[152:155], v164
	ds_read_b128 v[156:159], v164 offset:1024
	ds_read_b128 v[160:163], v164 offset:2048
	ds_read_b128 v[164:167], v164 offset:3072
	v_lshl_add_u64 v[192:193], s[22:23], 0, v[134:135]
	s_add_i32 m0, s37, 0xc000
	ds_read_b128 v[168:171], v209
	ds_read_b128 v[172:175], v209 offset:1024
	ds_read_b128 v[176:179], v209 offset:2048
	ds_read_b128 v[180:183], v209 offset:3072
	ds_read_b128 v[184:187], v209 offset:4096
	ds_read_b128 v[188:191], v209 offset:5120
	ds_read_b128 v[196:199], v209 offset:6144
	ds_read_b128 v[202:205], v209 offset:7168
	global_load_lds_dwordx4 v[192:193], off
	v_lshl_add_u64 v[192:193], s[22:23], 0, v[132:133]
	s_add_i32 m0, s37, 0xe000
	s_nop 0
	global_load_lds_dwordx4 v[192:193], off
	s_waitcnt vmcnt(8)
	s_waitcnt lgkmcnt(0)
	s_barrier
	s_waitcnt lgkmcnt(0)
	v_mfma_f32_16x16x32_bf16 v[126:129], v[136:139], v[168:171], v[126:129]
	v_mfma_f32_16x16x32_bf16 v[122:125], v[144:147], v[168:171], v[122:125]
	v_mfma_f32_16x16x32_bf16 v[108:111], v[136:139], v[176:179], v[108:111]
	v_mfma_f32_16x16x32_bf16 v[104:107], v[144:147], v[176:179], v[104:107]
	v_mfma_f32_16x16x32_bf16 v[92:95], v[136:139], v[184:187], v[92:95]
	v_mfma_f32_16x16x32_bf16 v[88:91], v[144:147], v[184:187], v[88:91]
	v_mfma_f32_16x16x32_bf16 v[76:79], v[136:139], v[196:199], v[76:79]
	v_mfma_f32_16x16x32_bf16 v[72:75], v[144:147], v[196:199], v[72:75]
	v_mfma_f32_16x16x32_bf16 v[126:129], v[140:143], v[172:175], v[126:129]
	v_mfma_f32_16x16x32_bf16 v[122:125], v[148:151], v[172:175], v[122:125]
	v_mfma_f32_16x16x32_bf16 v[108:111], v[140:143], v[180:183], v[108:111]
	v_mfma_f32_16x16x32_bf16 v[104:107], v[148:151], v[180:183], v[104:107]
	v_mfma_f32_16x16x32_bf16 v[92:95], v[140:143], v[188:191], v[92:95]
	v_mfma_f32_16x16x32_bf16 v[88:91], v[148:151], v[188:191], v[88:91]
	v_mfma_f32_16x16x32_bf16 v[76:79], v[140:143], v[202:205], v[76:79]
	v_mfma_f32_16x16x32_bf16 v[72:75], v[148:151], v[202:205], v[72:75]
	v_mfma_f32_16x16x32_bf16 v[118:121], v[152:155], v[168:171], v[118:121]
	v_mfma_f32_16x16x32_bf16 v[114:117], v[160:163], v[168:171], v[114:117]
	v_mfma_f32_16x16x32_bf16 v[100:103], v[152:155], v[176:179], v[100:103]
	v_mfma_f32_16x16x32_bf16 v[96:99], v[160:163], v[176:179], v[96:99]
	v_mfma_f32_16x16x32_bf16 v[84:87], v[152:155], v[184:187], v[84:87]
	v_mfma_f32_16x16x32_bf16 v[80:83], v[160:163], v[184:187], v[80:83]
	v_mfma_f32_16x16x32_bf16 v[68:71], v[152:155], v[196:199], v[68:71]
	v_mfma_f32_16x16x32_bf16 v[64:67], v[160:163], v[196:199], v[64:67]
	v_mfma_f32_16x16x32_bf16 v[118:121], v[156:159], v[172:175], v[118:121]
	v_mfma_f32_16x16x32_bf16 v[114:117], v[164:167], v[172:175], v[114:117]
	v_mfma_f32_16x16x32_bf16 v[100:103], v[156:159], v[180:183], v[100:103]
	v_mfma_f32_16x16x32_bf16 v[96:99], v[164:167], v[180:183], v[96:99]
	v_mfma_f32_16x16x32_bf16 v[84:87], v[156:159], v[188:191], v[84:87]
	v_mfma_f32_16x16x32_bf16 v[80:83], v[164:167], v[188:191], v[80:83]
	v_mfma_f32_16x16x32_bf16 v[68:71], v[156:159], v[202:205], v[68:71]
	v_mfma_f32_16x16x32_bf16 v[64:67], v[164:167], v[202:205], v[64:67]
	s_barrier
	s_add_i32 s22, s52, s30
	v_lshl_add_u64 v[192:193], s[26:27], 0, v[112:113]
	s_mov_b32 m0, s22
	ds_read_b128 v[168:171], v209 offset:16384
	ds_read_b128 v[172:175], v209 offset:17408
	ds_read_b128 v[176:179], v209 offset:18432
	ds_read_b128 v[180:183], v209 offset:19456
	ds_read_b128 v[184:187], v209 offset:20480
	ds_read_b128 v[188:191], v209 offset:21504
	ds_read_b128 v[196:199], v209 offset:22528
	ds_read_b128 v[202:205], v209 offset:23552
	global_load_lds_dwordx4 v[192:193], off
	s_add_i32 m0, s22, 0x2000
	s_add_u32 s22, s26, 0x160000
	v_lshl_add_u64 v[210:211], s[26:27], 0, v[130:131]
	s_addc_u32 s23, s27, 0
	s_add_i32 s52, s53, s30
	global_load_lds_dwordx4 v[210:211], off
	v_lshl_add_u64 v[212:213], s[22:23], 0, v[112:113]
	s_mov_b32 m0, s52
	v_lshl_add_u64 v[214:215], s[28:29], 0, v[130:131]
	global_load_lds_dwordx4 v[212:213], off
	v_lshl_add_u64 v[212:213], s[22:23], 0, v[130:131]
	s_add_i32 m0, s52, 0x2000
	s_nop 0
	global_load_lds_dwordx4 v[212:213], off
	v_lshl_add_u64 v[212:213], s[28:29], 0, v[112:113]
	s_mov_b32 m0, s37
	s_nop 0
	global_load_lds_dwordx4 v[212:213], off
	s_mov_b32 m0, s38
	s_nop 0
	global_load_lds_dwordx4 v[214:215], off
	s_waitcnt vmcnt(8)
	s_waitcnt lgkmcnt(0)
	s_barrier
; #define PG8_STAGE(bufoff, gbase, voff) do { _Pragma("unroll") for (int _i = 0; _i < 2; ++_i) \
;         __builtin_amdgcn_global_load_lds((const unsigned*)((const char*)(gbase) + (voff)[_i]), (PG8_LAS unsigned*)(lds + (bufoff) + ldsw + _i * 8192), 16, 0, 0); } while (0)
; #define PG8_LDA(dst, b, h) do { _Pragma("unroll") for (int m = 0; m < 4; ++m) _Pragma("unroll") for (int k = 0; k < 2; ++k) dst[m][k] = *(const PG8_LAS bf16x8*)(lds + PG8_SA(b, h) + aoff + m * 2048 + k * 1024); } while (0)
; #define PG8_LDB(dst, b, h) do { _Pragma("unroll") for (int n = 0; n < 2; ++n) _Pragma("unroll") for (int k = 0; k < 2; ++k) dst[n][k] = *(const PG8_LAS bf16x8*)(lds + PG8_SB(b, h) + boff + n * 2048 + k * 1024); } while (0)
; #define PG8_MMA(ai, bj, At, Bt) do { __builtin_amdgcn_s_setprio(1); _Pragma("unroll") for (int m = 0; m < 4; ++m) _Pragma("unroll") for (int n = 0; n < 2; ++n) _Pragma("unroll") for (int k = 0; k < 2; ++k) \
;         acc[ai][bj][m][n] = __builtin_amdgcn_mfma_f32_16x16x32_bf16(Bt[n][k], At[m][k], acc[ai][bj][m][n], 0, 0, 0); __builtin_amdgcn_s_setprio(0); } while (0)
; #define PG8_WAIT_V(n) asm volatile("s_waitcnt vmcnt(" #n ")" ::: "memory")
; #define PG8_WAIT_L(n) asm volatile("s_waitcnt lgkmcnt(" #n ")" ::: "memory")
; #define PG8_BAR __builtin_amdgcn_s_barrier()
; #define PG8_SCHED __builtin_amdgcn_sched_barrier(0)
; template <class Epi, class Sched, bool ALIGN_EPI = false, bool SP2 = false>
; __device__ __forceinline__ void gemm_phase(PG8_LAS unsigned char* lds, const Gemm g, const Sched& S, const Epi& E) {
;     ...
;             PG8_WAIT_V(8); PG8_WAIT_L(0); PG8_BAR; PG8_MMA(1, 0, At, B0); PG8_MMA(1, 1, At, B1); PG8_BAR; PG8_SCHED;
;             PG8_LDB(B0, 1, 0); PG8_LDB(B1, 1, 1); PG8_SCHED; PG8_LDA(At, 1, 0); PG8_STAGE(PG8_SA(0, 1), a2 + hstepA, voffA);
;             PG8_WAIT_V(8); PG8_WAIT_L(0); PG8_BAR; PG8_MMA(0, 0, At, B0); PG8_MMA(0, 1, At, B1); PG8_BAR; PG8_SCHED;
;             PG8_LDA(At, 1, 1); PG8_STAGE(PG8_SB(1, 0), b3, voffB); PG8_STAGE(PG8_SB(1, 1), b3 + hstepB, voffB); PG8_STAGE(PG8_SA(1, 0), a3, voffA);
	s_waitcnt lgkmcnt(0)
	v_mfma_f32_16x16x32_bf16 v[60:63], v[136:139], v[168:171], v[60:63]
	v_mfma_f32_16x16x32_bf16 v[56:59], v[144:147], v[168:171], v[56:59]
	v_mfma_f32_16x16x32_bf16 v[44:47], v[136:139], v[176:179], v[44:47]
	v_mfma_f32_16x16x32_bf16 v[40:43], v[144:147], v[176:179], v[40:43]
	v_mfma_f32_16x16x32_bf16 v[28:31], v[136:139], v[184:187], v[28:31]
	v_mfma_f32_16x16x32_bf16 v[24:27], v[144:147], v[184:187], v[24:27]
	v_mfma_f32_16x16x32_bf16 v[12:15], v[136:139], v[196:199], v[12:15]
	v_mfma_f32_16x16x32_bf16 v[8:11], v[144:147], v[196:199], v[8:11]
	v_mfma_f32_16x16x32_bf16 v[60:63], v[140:143], v[172:175], v[60:63]
	v_mfma_f32_16x16x32_bf16 v[56:59], v[148:151], v[172:175], v[56:59]
	v_mfma_f32_16x16x32_bf16 v[44:47], v[140:143], v[180:183], v[44:47]
	v_mfma_f32_16x16x32_bf16 v[40:43], v[148:151], v[180:183], v[40:43]
	v_mfma_f32_16x16x32_bf16 v[28:31], v[140:143], v[188:191], v[28:31]
	v_mfma_f32_16x16x32_bf16 v[24:27], v[148:151], v[188:191], v[24:27]
	v_mfma_f32_16x16x32_bf16 v[12:15], v[140:143], v[202:205], v[12:15]
	v_mfma_f32_16x16x32_bf16 v[8:11], v[148:151], v[202:205], v[8:11]
	v_mfma_f32_16x16x32_bf16 v[52:55], v[152:155], v[168:171], v[52:55]
	v_mfma_f32_16x16x32_bf16 v[48:51], v[160:163], v[168:171], v[48:51]
	v_mfma_f32_16x16x32_bf16 v[36:39], v[152:155], v[176:179], v[36:39]
	v_mfma_f32_16x16x32_bf16 v[32:35], v[160:163], v[176:179], v[32:35]
	v_mfma_f32_16x16x32_bf16 v[20:23], v[152:155], v[184:187], v[20:23]
	v_mfma_f32_16x16x32_bf16 v[16:19], v[160:163], v[184:187], v[16:19]
	v_mfma_f32_16x16x32_bf16 v[4:7], v[152:155], v[196:199], v[4:7]
	v_mfma_f32_16x16x32_bf16 v[0:3], v[160:163], v[196:199], v[0:3]
	v_mfma_f32_16x16x32_bf16 v[52:55], v[156:159], v[172:175], v[52:55]
	v_mfma_f32_16x16x32_bf16 v[48:51], v[164:167], v[172:175], v[48:51]
	v_mfma_f32_16x16x32_bf16 v[36:39], v[156:159], v[180:183], v[36:39]
	v_mfma_f32_16x16x32_bf16 v[32:35], v[164:167], v[180:183], v[32:35]
	v_mfma_f32_16x16x32_bf16 v[20:23], v[156:159], v[188:191], v[20:23]
	v_mfma_f32_16x16x32_bf16 v[16:19], v[164:167], v[188:191], v[16:19]
	v_mfma_f32_16x16x32_bf16 v[4:7], v[156:159], v[202:205], v[4:7]
	v_mfma_f32_16x16x32_bf16 v[0:3], v[164:167], v[202:205], v[0:3]
	s_barrier
	s_add_i32 s52, 0, 0x18000
	s_add_i32 s53, 0, 0x1c000
	v_add_u32_e32 v148, s52, v207
	v_add_u32_e32 v164, s53, v207
	ds_read_b128 v[136:139], v148
	ds_read_b128 v[140:143], v148 offset:1024
	ds_read_b128 v[144:147], v148 offset:2048
	ds_read_b128 v[148:151], v148 offset:3072
	ds_read_b128 v[152:155], v164
	ds_read_b128 v[156:159], v164 offset:1024
	ds_read_b128 v[160:163], v164 offset:2048
	ds_read_b128 v[164:167], v164 offset:3072
	s_add_u32 s22, s28, 0x160000
	s_addc_u32 s23, s29, 0
	s_mov_b32 m0, s39
	v_lshl_add_u64 v[216:217], s[22:23], 0, v[112:113]
	ds_read_b128 v[168:171], v209 offset:32768
	ds_read_b128 v[172:175], v209 offset:33792
	ds_read_b128 v[176:179], v209 offset:34816
	ds_read_b128 v[180:183], v209 offset:35840
	ds_read_b128 v[184:187], v209 offset:36864
	ds_read_b128 v[188:191], v209 offset:37888
	ds_read_b128 v[196:199], v209 offset:38912
	ds_read_b128 v[202:205], v209 offset:39936
	global_load_lds_dwordx4 v[216:217], off
	v_lshl_add_u64 v[216:217], s[22:23], 0, v[130:131]
	s_mov_b32 m0, s40
	s_nop 0
	global_load_lds_dwordx4 v[216:217], off
	s_waitcnt vmcnt(8)
	s_waitcnt lgkmcnt(0)
	s_barrier
	s_waitcnt lgkmcnt(0)
	v_mfma_f32_16x16x32_bf16 v[126:129], v[136:139], v[168:171], v[126:129]
	v_mfma_f32_16x16x32_bf16 v[122:125], v[144:147], v[168:171], v[122:125]
	v_mfma_f32_16x16x32_bf16 v[108:111], v[136:139], v[176:179], v[108:111]
	v_mfma_f32_16x16x32_bf16 v[104:107], v[144:147], v[176:179], v[104:107]
	v_mfma_f32_16x16x32_bf16 v[92:95], v[136:139], v[184:187], v[92:95]
	v_mfma_f32_16x16x32_bf16 v[88:91], v[144:147], v[184:187], v[88:91]
	v_mfma_f32_16x16x32_bf16 v[76:79], v[136:139], v[196:199], v[76:79]
	v_mfma_f32_16x16x32_bf16 v[72:75], v[144:147], v[196:199], v[72:75]
	v_mfma_f32_16x16x32_bf16 v[126:129], v[140:143], v[172:175], v[126:129]
	v_mfma_f32_16x16x32_bf16 v[122:125], v[148:151], v[172:175], v[122:125]
	v_mfma_f32_16x16x32_bf16 v[108:111], v[140:143], v[180:183], v[108:111]
	v_mfma_f32_16x16x32_bf16 v[104:107], v[148:151], v[180:183], v[104:107]
	v_mfma_f32_16x16x32_bf16 v[92:95], v[140:143], v[188:191], v[92:95]
	v_mfma_f32_16x16x32_bf16 v[88:91], v[148:151], v[188:191], v[88:91]
	v_mfma_f32_16x16x32_bf16 v[76:79], v[140:143], v[202:205], v[76:79]
	v_mfma_f32_16x16x32_bf16 v[72:75], v[148:151], v[202:205], v[72:75]
	v_mfma_f32_16x16x32_bf16 v[118:121], v[152:155], v[168:171], v[118:121]
	v_mfma_f32_16x16x32_bf16 v[114:117], v[160:163], v[168:171], v[114:117]
	v_mfma_f32_16x16x32_bf16 v[100:103], v[152:155], v[176:179], v[100:103]
	v_mfma_f32_16x16x32_bf16 v[96:99], v[160:163], v[176:179], v[96:99]
	v_mfma_f32_16x16x32_bf16 v[84:87], v[152:155], v[184:187], v[84:87]
	v_mfma_f32_16x16x32_bf16 v[80:83], v[160:163], v[184:187], v[80:83]
	v_mfma_f32_16x16x32_bf16 v[68:71], v[152:155], v[196:199], v[68:71]
	v_mfma_f32_16x16x32_bf16 v[64:67], v[160:163], v[196:199], v[64:67]
	v_mfma_f32_16x16x32_bf16 v[118:121], v[156:159], v[172:175], v[118:121]
	v_mfma_f32_16x16x32_bf16 v[114:117], v[164:167], v[172:175], v[114:117]
	v_mfma_f32_16x16x32_bf16 v[100:103], v[156:159], v[180:183], v[100:103]
	v_mfma_f32_16x16x32_bf16 v[96:99], v[164:167], v[180:183], v[96:99]
	v_mfma_f32_16x16x32_bf16 v[84:87], v[156:159], v[188:191], v[84:87]
	v_mfma_f32_16x16x32_bf16 v[80:83], v[164:167], v[188:191], v[80:83]
	v_mfma_f32_16x16x32_bf16 v[68:71], v[156:159], v[202:205], v[68:71]
	v_mfma_f32_16x16x32_bf16 v[64:67], v[164:167], v[202:205], v[64:67]
	s_barrier
; #define PG8_STAGE(bufoff, gbase, voff) do { _Pragma("unroll") for (int _i = 0; _i < 2; ++_i) \
;         __builtin_amdgcn_global_load_lds((const unsigned*)((const char*)(gbase) + (voff)[_i]), (PG8_LAS unsigned*)(lds + (bufoff) + ldsw + _i * 8192), 16, 0, 0); } while (0)
; #define PG8_LDA(dst, b, h) do { _Pragma("unroll") for (int m = 0; m < 4; ++m) _Pragma("unroll") for (int k = 0; k < 2; ++k) dst[m][k] = *(const PG8_LAS bf16x8*)(lds + PG8_SA(b, h) + aoff + m * 2048 + k * 1024); } while (0)
; #define PG8_MMA(ai, bj, At, Bt) do { __builtin_amdgcn_s_setprio(1); _Pragma("unroll") for (int m = 0; m < 4; ++m) _Pragma("unroll") for (int n = 0; n < 2; ++n) _Pragma("unroll") for (int k = 0; k < 2; ++k) \
;         acc[ai][bj][m][n] = __builtin_amdgcn_mfma_f32_16x16x32_bf16(Bt[n][k], At[m][k], acc[ai][bj][m][n], 0, 0, 0); __builtin_amdgcn_s_setprio(0); } while (0)
; #define PG8_WAIT_V(n) asm volatile("s_waitcnt vmcnt(" #n ")" ::: "memory")
; #define PG8_WAIT_L(n) asm volatile("s_waitcnt lgkmcnt(" #n ")" ::: "memory")
; #define PG8_BAR __builtin_amdgcn_s_barrier()
; #define PG8_SCHED __builtin_amdgcn_sched_barrier(0)
; template <class Epi, class Sched, bool ALIGN_EPI = false, bool SP2 = false>
; __device__ __forceinline__ void gemm_phase(PG8_LAS unsigned char* lds, const Gemm g, const Sched& S, const Epi& E) {
;     ...
;             PG8_LDA(At, 1, 1); PG8_STAGE(PG8_SB(1, 0), b3, voffB); PG8_STAGE(PG8_SB(1, 1), b3 + hstepB, voffB); PG8_STAGE(PG8_SA(1, 0), a3, voffA);
;             PG8_WAIT_V(8); PG8_WAIT_L(0); PG8_BAR; PG8_MMA(1, 0, At, B0); PG8_MMA(1, 1, At, B1); PG8_BAR; PG8_SCHED;
	s_add_i32 s22, s52, s30
	v_lshl_add_u64 v[192:193], v[192:193], 0, s[2:3]
	s_mov_b32 m0, s22
	ds_read_b128 v[168:171], v209 offset:49152
	ds_read_b128 v[172:175], v209 offset:50176
	ds_read_b128 v[176:179], v209 offset:51200
	ds_read_b128 v[180:183], v209 offset:52224
	ds_read_b128 v[184:187], v209 offset:53248
	ds_read_b128 v[188:191], v209 offset:54272
	ds_read_b128 v[196:199], v209 offset:55296
	ds_read_b128 v[202:205], v209 offset:56320
	global_load_lds_dwordx4 v[192:193], off
	s_add_i32 m0, s22, 0x2000
	s_add_u32 s22, s26, 0x160080
	v_lshl_add_u64 v[192:193], v[210:211], 0, s[2:3]
	s_addc_u32 s23, s27, 0
	s_add_i32 s26, s53, s30
	global_load_lds_dwordx4 v[192:193], off
	v_lshl_add_u64 v[192:193], s[22:23], 0, v[112:113]
	s_mov_b32 m0, s26
	s_nop 0
	global_load_lds_dwordx4 v[192:193], off
	v_lshl_add_u64 v[192:193], s[22:23], 0, v[130:131]
	s_add_i32 m0, s26, 0x2000
	s_nop 0
	global_load_lds_dwordx4 v[192:193], off
	v_lshl_add_u64 v[192:193], v[212:213], 0, s[2:3]
	s_mov_b32 m0, s42
	s_nop 0
	global_load_lds_dwordx4 v[192:193], off
	v_lshl_add_u64 v[192:193], v[214:215], 0, s[2:3]
	s_mov_b32 m0, s43
	s_nop 0
	global_load_lds_dwordx4 v[192:193], off
	s_waitcnt vmcnt(8)
	s_waitcnt lgkmcnt(0)
	s_barrier
	s_waitcnt lgkmcnt(0)
	v_mfma_f32_16x16x32_bf16 v[60:63], v[136:139], v[168:171], v[60:63]
	v_mfma_f32_16x16x32_bf16 v[56:59], v[144:147], v[168:171], v[56:59]
	v_mfma_f32_16x16x32_bf16 v[44:47], v[136:139], v[176:179], v[44:47]
	v_mfma_f32_16x16x32_bf16 v[40:43], v[144:147], v[176:179], v[40:43]
	v_mfma_f32_16x16x32_bf16 v[28:31], v[136:139], v[184:187], v[28:31]
	v_mfma_f32_16x16x32_bf16 v[24:27], v[144:147], v[184:187], v[24:27]
	v_mfma_f32_16x16x32_bf16 v[12:15], v[136:139], v[196:199], v[12:15]
	v_mfma_f32_16x16x32_bf16 v[8:11], v[144:147], v[196:199], v[8:11]
	v_mfma_f32_16x16x32_bf16 v[60:63], v[140:143], v[172:175], v[60:63]
	v_mfma_f32_16x16x32_bf16 v[56:59], v[148:151], v[172:175], v[56:59]
	v_mfma_f32_16x16x32_bf16 v[44:47], v[140:143], v[180:183], v[44:47]
	v_mfma_f32_16x16x32_bf16 v[40:43], v[148:151], v[180:183], v[40:43]
	v_mfma_f32_16x16x32_bf16 v[28:31], v[140:143], v[188:191], v[28:31]
	v_mfma_f32_16x16x32_bf16 v[24:27], v[148:151], v[188:191], v[24:27]
	v_mfma_f32_16x16x32_bf16 v[12:15], v[140:143], v[202:205], v[12:15]
	v_mfma_f32_16x16x32_bf16 v[8:11], v[148:151], v[202:205], v[8:11]
	v_mfma_f32_16x16x32_bf16 v[52:55], v[152:155], v[168:171], v[52:55]
	v_mfma_f32_16x16x32_bf16 v[48:51], v[160:163], v[168:171], v[48:51]
	v_mfma_f32_16x16x32_bf16 v[36:39], v[152:155], v[176:179], v[36:39]
	v_mfma_f32_16x16x32_bf16 v[32:35], v[160:163], v[176:179], v[32:35]
	v_mfma_f32_16x16x32_bf16 v[20:23], v[152:155], v[184:187], v[20:23]
	v_mfma_f32_16x16x32_bf16 v[16:19], v[160:163], v[184:187], v[16:19]
	v_mfma_f32_16x16x32_bf16 v[4:7], v[152:155], v[196:199], v[4:7]
	v_mfma_f32_16x16x32_bf16 v[0:3], v[160:163], v[196:199], v[0:3]
	v_mfma_f32_16x16x32_bf16 v[52:55], v[156:159], v[172:175], v[52:55]
	v_mfma_f32_16x16x32_bf16 v[48:51], v[164:167], v[172:175], v[48:51]
	v_mfma_f32_16x16x32_bf16 v[36:39], v[156:159], v[180:183], v[36:39]
	v_mfma_f32_16x16x32_bf16 v[32:35], v[164:167], v[180:183], v[32:35]
	v_mfma_f32_16x16x32_bf16 v[20:23], v[156:159], v[188:191], v[20:23]
	v_mfma_f32_16x16x32_bf16 v[16:19], v[164:167], v[188:191], v[16:19]
	v_mfma_f32_16x16x32_bf16 v[4:7], v[156:159], v[202:205], v[4:7]
	v_mfma_f32_16x16x32_bf16 v[0:3], v[164:167], v[202:205], v[0:3]
	s_barrier
	s_add_i32 s51, s51, 2
	s_add_u32 s49, s49, 0x100
	s_addc_u32 s50, s50, 0
	s_cmpk_gt_u32 s51, 0x55
	s_mov_b64 s[22:23], s[24:25]
	s_cbranch_scc0 .LBB0_792
	s_and_b64 vcc, exec, s[18:19]
	s_cbranch_vccz .LBB0_795
	s_barrier
